# MLP hidden U stored as 16 column panels [panel][row][256] (row pitch 512 B): P6/P11 epilogues write it, P7/P12 A-operand LDS-DMA addressing reads it (better DRAM locality for the K=4096 GEMM A loads)
# speedup vs baseline: 1.0263x; 1.0077x over previous
.LBB0_779:
	v_lshl_add_u32 v148, s4, 8, v150
	v_ashrrev_i32_e32 v149, 31, v148
	v_lshlrev_b64 v[146:147], 6, v[148:149]
	v_lshl_add_u64 v[146:147], v[136:137], 0, v[146:147]
	s_mov_b64 s[98:99], 0x2000
	global_load_dwordx4 v[160:163], v[146:147], off
	global_load_dwordx4 v[206:209], v[146:147], off offset:1024
	global_load_dwordx4 v[210:213], v[146:147], off offset:2048
	global_load_dwordx4 v[214:217], v[146:147], off offset:3072
	v_lshl_add_u64 v[234:235], v[146:147], 0, s[98:99]
	global_load_dwordx4 v[218:221], v[234:235], off
	global_load_dwordx4 v[222:225], v[234:235], off offset:1024
	global_load_dwordx4 v[226:229], v[234:235], off offset:2048
	global_load_dwordx4 v[230:233], v[234:235], off offset:3072
	v_and_b32_e32 v159, 64, v156
	v_xor_b32_e32 v147, 16, v156
	v_add_u32_e32 v167, 64, v159
	v_cmp_lt_i32_e32 vcc, v147, v167
	v_xor_b32_e32 v166, 32, v156
	v_lshl_or_b32 v146, s5, 23, v152
	v_cndmask_b32_e32 v147, v156, v147, vcc
	v_lshlrev_b32_e32 v159, 2, v147
	v_cmp_lt_i32_e32 vcc, v166, v167
	v_ashrrev_i32_e32 v147, 31, v146
	v_lshlrev_b64 v[146:147], 1, v[146:147]
	s_waitcnt vmcnt(7)
	v_mov_b32_e32 v164, v161
	v_mov_b32_e32 v165, v162
	v_mov_b32_e32 v161, v163
	v_pk_add_f32 v[160:161], v[164:165], v[160:161]
	v_lshlrev_b64 v[164:165], 9, v[148:149]
	v_add_f32_e32 v161, v160, v161
	ds_bpermute_b32 v162, v159, v161
	v_cndmask_b32_e32 v160, v156, v166, vcc
	v_lshlrev_b32_e32 v160, 2, v160
	v_lshl_add_u64 v[164:165], s[10:11], 0, v[164:165]
	v_lshl_add_u64 v[164:165], v[164:165], 0, v[146:147]
	s_waitcnt lgkmcnt(0)
	v_add_f32_e32 v161, v161, v162
	ds_bpermute_b32 v166, v160, v161
	v_or_b32_e32 v162, 16, v148
	v_ashrrev_i32_e32 v163, 31, v162
	s_waitcnt lgkmcnt(0)
	v_add_f32_e32 v149, v161, v166
	v_fmamk_f32 v149, v149, 0x3a800000, v157
	v_lshlrev_b64 v[166:167], 6, v[162:163]
	v_lshl_add_u64 v[166:167], v[136:137], 0, v[166:167]
	v_rsq_f32_e32 v161, v149
	v_mul_f32_e32 v170, 0.5, v149
	v_mul_f32_e32 v168, v161, v161
	v_fma_f32 v170, -v170, v168, 0.5
	v_fma_f32 v168, v161, v170, v161
	v_pk_mul_f32 v[126:127], v[126:127], v[168:169] op_sel_hi:[1,0]
	v_pk_mul_f32 v[124:125], v[124:125], v[168:169] op_sel_hi:[1,0]
	v_pk_mul_f32 v[122:123], v[122:123], v[168:169] op_sel_hi:[1,0]
	v_pk_mul_f32 v[120:121], v[120:121], v[168:169] op_sel_hi:[1,0]
	v_pk_mul_f32 v[114:115], v[114:115], v[168:169] op_sel_hi:[1,0]
	v_pk_mul_f32 v[112:113], v[112:113], v[168:169] op_sel_hi:[1,0]
	v_pk_mul_f32 v[118:119], v[118:119], v[168:169] op_sel_hi:[1,0]
	v_pk_mul_f32 v[116:117], v[116:117], v[168:169] op_sel_hi:[1,0]
	v_max_f32_e32 v124, 0, v124
	v_max_f32_e32 v120, 0, v120
	v_max_f32_e32 v125, 0, v125
	v_max_f32_e32 v121, 0, v121
	v_max_f32_e32 v126, 0, v126
	v_max_f32_e32 v122, 0, v122
	v_max_f32_e32 v127, 0, v127
	v_max_f32_e32 v123, 0, v123
	v_max_f32_e32 v112, 0, v112
	v_max_f32_e32 v113, 0, v113
	v_max_f32_e32 v114, 0, v114
	v_max_f32_e32 v115, 0, v115
	v_max_f32_e32 v116, 0, v116
	v_max_f32_e32 v117, 0, v117
	v_max_f32_e32 v118, 0, v118
	v_max_f32_e32 v119, 0, v119
	v_mul_f32_e32 v124, v124, v124
	v_mul_f32_e32 v120, v120, v120
	v_mul_f32_e32 v125, v125, v125
	v_mul_f32_e32 v121, v121, v121
	v_mul_f32_e32 v126, v126, v126
	v_mul_f32_e32 v122, v122, v122
	v_mul_f32_e32 v127, v127, v127
	v_mul_f32_e32 v123, v123, v123
	v_mul_f32_e32 v149, v112, v112
	v_mul_f32_e32 v161, v113, v113
	v_mul_f32_e32 v168, v114, v114
	v_mul_f32_e32 v169, v115, v115
	v_cvt_pk_bf16_f32 v112, v124, v125
	v_cvt_pk_bf16_f32 v113, v126, v127
	v_cvt_pk_bf16_f32 v114, v120, v121
	v_cvt_pk_bf16_f32 v115, v122, v123
	v_mul_f32_e32 v116, v116, v116
	v_mul_f32_e32 v117, v117, v117
	v_mul_f32_e32 v118, v118, v118
	v_mul_f32_e32 v119, v119, v119
	global_store_dwordx4 v[164:165], v[112:115], off
	s_nop 1
	v_cvt_pk_bf16_f32 v112, v116, v117
	v_cvt_pk_bf16_f32 v113, v118, v119
	v_cvt_pk_bf16_f32 v114, v149, v161
	v_cvt_pk_bf16_f32 v115, v168, v169
	global_store_dwordx4 v[164:165], v[112:115], off offset:64
	s_waitcnt vmcnt(8)
	s_nop 1
	v_mov_b32_e32 v112, v206
	v_mov_b32_e32 v113, v207
	v_mov_b32_e32 v114, v208
	v_mov_b32_e32 v115, v209
	v_mov_b32_e32 v116, v113
	v_mov_b32_e32 v117, v114
	v_mov_b32_e32 v113, v115
	v_pk_add_f32 v[112:113], v[116:117], v[112:113]
	v_lshlrev_b64 v[114:115], 9, v[162:163]
	v_add_f32_e32 v112, v112, v113
	ds_bpermute_b32 v113, v159, v112
	v_lshl_add_u64 v[114:115], s[10:11], 0, v[114:115]
	v_lshl_add_u64 v[114:115], v[114:115], 0, v[146:147]
	s_waitcnt lgkmcnt(0)
	v_add_f32_e32 v116, v112, v113
	ds_bpermute_b32 v117, v160, v116
	v_or_b32_e32 v112, 32, v148
	v_ashrrev_i32_e32 v113, 31, v112
	s_waitcnt lgkmcnt(0)
	v_add_f32_e32 v116, v116, v117
	v_fmamk_f32 v116, v116, 0x3a800000, v157
	v_mov_b32_e32 v118, v116
	v_lshlrev_b64 v[116:117], 6, v[112:113]
	v_lshl_add_u64 v[116:117], v[136:137], 0, v[116:117]
	v_rsq_f32_e32 v119, v118
	v_mul_f32_e32 v120, 0.5, v118
	v_mul_f32_e32 v118, v119, v119
	v_fma_f32 v120, -v120, v118, 0.5
	v_fma_f32 v118, v119, v120, v119
	v_pk_mul_f32 v[110:111], v[110:111], v[118:119] op_sel_hi:[1,0]
	v_pk_mul_f32 v[108:109], v[108:109], v[118:119] op_sel_hi:[1,0]
	v_pk_mul_f32 v[106:107], v[106:107], v[118:119] op_sel_hi:[1,0]
	v_pk_mul_f32 v[104:105], v[104:105], v[118:119] op_sel_hi:[1,0]
	v_pk_mul_f32 v[98:99], v[98:99], v[118:119] op_sel_hi:[1,0]
	v_pk_mul_f32 v[96:97], v[96:97], v[118:119] op_sel_hi:[1,0]
	v_pk_mul_f32 v[102:103], v[102:103], v[118:119] op_sel_hi:[1,0]
	v_pk_mul_f32 v[100:101], v[100:101], v[118:119] op_sel_hi:[1,0]
	v_max_f32_e32 v108, 0, v108
	v_max_f32_e32 v104, 0, v104
	v_max_f32_e32 v109, 0, v109
	v_max_f32_e32 v105, 0, v105
	v_max_f32_e32 v110, 0, v110
	v_max_f32_e32 v106, 0, v106
	v_max_f32_e32 v111, 0, v111
	v_max_f32_e32 v107, 0, v107
	v_max_f32_e32 v96, 0, v96
	v_max_f32_e32 v97, 0, v97
	v_max_f32_e32 v98, 0, v98
	v_max_f32_e32 v99, 0, v99
	v_max_f32_e32 v100, 0, v100
	v_max_f32_e32 v101, 0, v101
	v_max_f32_e32 v102, 0, v102
	v_max_f32_e32 v103, 0, v103
	v_mul_f32_e32 v108, v108, v108
	v_mul_f32_e32 v104, v104, v104
	v_mul_f32_e32 v109, v109, v109
	v_mul_f32_e32 v105, v105, v105
	v_mul_f32_e32 v110, v110, v110
	v_mul_f32_e32 v106, v106, v106
	v_mul_f32_e32 v111, v111, v111
	v_mul_f32_e32 v107, v107, v107
	v_mul_f32_e32 v118, v96, v96
	v_mul_f32_e32 v119, v97, v97
	v_mul_f32_e32 v120, v98, v98
	v_mul_f32_e32 v121, v99, v99
	v_cvt_pk_bf16_f32 v96, v108, v109
	v_cvt_pk_bf16_f32 v97, v110, v111
	v_cvt_pk_bf16_f32 v98, v104, v105
	v_cvt_pk_bf16_f32 v99, v106, v107
	v_mul_f32_e32 v100, v100, v100
	v_mul_f32_e32 v101, v101, v101
	v_mul_f32_e32 v102, v102, v102
	v_mul_f32_e32 v103, v103, v103
	global_store_dwordx4 v[114:115], v[96:99], off
	s_nop 1
	v_cvt_pk_bf16_f32 v96, v100, v101
	v_cvt_pk_bf16_f32 v97, v102, v103
	v_cvt_pk_bf16_f32 v98, v118, v119
	v_cvt_pk_bf16_f32 v99, v120, v121
	global_store_dwordx4 v[114:115], v[96:99], off offset:64
	s_waitcnt vmcnt(9)
	s_nop 1
	v_mov_b32_e32 v96, v210
	v_mov_b32_e32 v97, v211
	v_mov_b32_e32 v98, v212
	v_mov_b32_e32 v99, v213
	v_mov_b32_e32 v100, v97
	v_mov_b32_e32 v101, v98
	v_mov_b32_e32 v97, v99
	v_pk_add_f32 v[96:97], v[100:101], v[96:97]
	v_lshlrev_b64 v[98:99], 9, v[112:113]
	v_add_f32_e32 v96, v96, v97
	ds_bpermute_b32 v97, v159, v96
	v_lshl_add_u64 v[98:99], s[10:11], 0, v[98:99]
	v_lshl_add_u64 v[98:99], v[98:99], 0, v[146:147]
	s_waitcnt lgkmcnt(0)
	v_add_f32_e32 v100, v96, v97
	ds_bpermute_b32 v101, v160, v100
	v_or_b32_e32 v96, 48, v148
	v_ashrrev_i32_e32 v97, 31, v96
	s_waitcnt lgkmcnt(0)
	v_add_f32_e32 v100, v100, v101
	v_fmamk_f32 v100, v100, 0x3a800000, v157
	v_mov_b32_e32 v102, v100
	v_lshlrev_b64 v[100:101], 6, v[96:97]
	v_lshl_add_u64 v[100:101], v[136:137], 0, v[100:101]
	v_rsq_f32_e32 v103, v102
	v_mul_f32_e32 v104, 0.5, v102
	v_mul_f32_e32 v102, v103, v103
	v_fma_f32 v104, -v104, v102, 0.5
	v_fma_f32 v102, v103, v104, v103
	v_pk_mul_f32 v[94:95], v[94:95], v[102:103] op_sel_hi:[1,0]
	v_pk_mul_f32 v[92:93], v[92:93], v[102:103] op_sel_hi:[1,0]
	v_pk_mul_f32 v[90:91], v[90:91], v[102:103] op_sel_hi:[1,0]
	v_pk_mul_f32 v[88:89], v[88:89], v[102:103] op_sel_hi:[1,0]
	v_pk_mul_f32 v[82:83], v[82:83], v[102:103] op_sel_hi:[1,0]
	v_pk_mul_f32 v[80:81], v[80:81], v[102:103] op_sel_hi:[1,0]
	v_pk_mul_f32 v[86:87], v[86:87], v[102:103] op_sel_hi:[1,0]
	v_pk_mul_f32 v[84:85], v[84:85], v[102:103] op_sel_hi:[1,0]
	v_max_f32_e32 v92, 0, v92
	v_max_f32_e32 v88, 0, v88
	v_max_f32_e32 v93, 0, v93
	v_max_f32_e32 v89, 0, v89
	v_max_f32_e32 v94, 0, v94
	v_max_f32_e32 v90, 0, v90
	v_max_f32_e32 v95, 0, v95
	v_max_f32_e32 v91, 0, v91
	v_max_f32_e32 v80, 0, v80
	v_max_f32_e32 v81, 0, v81
	v_max_f32_e32 v82, 0, v82
	v_max_f32_e32 v83, 0, v83
	v_max_f32_e32 v84, 0, v84
	v_max_f32_e32 v85, 0, v85
	v_max_f32_e32 v86, 0, v86
	v_max_f32_e32 v87, 0, v87
	v_mul_f32_e32 v92, v92, v92
	v_mul_f32_e32 v88, v88, v88
	v_mul_f32_e32 v93, v93, v93
	v_mul_f32_e32 v89, v89, v89
	v_mul_f32_e32 v94, v94, v94
	v_mul_f32_e32 v90, v90, v90
	v_mul_f32_e32 v95, v95, v95
	v_mul_f32_e32 v91, v91, v91
	v_mul_f32_e32 v102, v80, v80
	v_mul_f32_e32 v103, v81, v81
	v_mul_f32_e32 v104, v82, v82
	v_mul_f32_e32 v105, v83, v83
	v_cvt_pk_bf16_f32 v80, v92, v93
	v_cvt_pk_bf16_f32 v81, v94, v95
	v_cvt_pk_bf16_f32 v82, v88, v89
	v_cvt_pk_bf16_f32 v83, v90, v91
	v_mul_f32_e32 v84, v84, v84
	v_mul_f32_e32 v85, v85, v85
	v_mul_f32_e32 v86, v86, v86
	v_mul_f32_e32 v87, v87, v87
	global_store_dwordx4 v[98:99], v[80:83], off
	s_nop 1
	v_cvt_pk_bf16_f32 v80, v84, v85
	v_cvt_pk_bf16_f32 v81, v86, v87
	v_cvt_pk_bf16_f32 v82, v102, v103
	v_cvt_pk_bf16_f32 v83, v104, v105
	global_store_dwordx4 v[98:99], v[80:83], off offset:64
	s_waitcnt vmcnt(10)
	s_nop 1
	v_mov_b32_e32 v80, v214
	v_mov_b32_e32 v81, v215
	v_mov_b32_e32 v82, v216
	v_mov_b32_e32 v83, v217
	v_mov_b32_e32 v84, v81
	v_mov_b32_e32 v85, v82
	v_mov_b32_e32 v81, v83
	v_pk_add_f32 v[80:81], v[84:85], v[80:81]
	v_lshlrev_b64 v[82:83], 9, v[96:97]
	v_add_f32_e32 v80, v80, v81
	ds_bpermute_b32 v81, v159, v80
	v_lshl_add_u64 v[82:83], s[10:11], 0, v[82:83]
	v_lshl_add_u64 v[82:83], v[82:83], 0, v[146:147]
	s_waitcnt lgkmcnt(0)
	v_add_f32_e32 v84, v80, v81
	ds_bpermute_b32 v85, v160, v84
	v_add_u32_e32 v80, 0x80, v148
	v_ashrrev_i32_e32 v81, 31, v80
	s_waitcnt lgkmcnt(0)
	v_add_f32_e32 v84, v84, v85
	v_fmamk_f32 v84, v84, 0x3a800000, v157
	v_mov_b32_e32 v86, v84
	v_lshlrev_b64 v[84:85], 6, v[80:81]
	v_lshl_add_u64 v[84:85], v[136:137], 0, v[84:85]
	v_rsq_f32_e32 v87, v86
	v_mul_f32_e32 v88, 0.5, v86
	v_mul_f32_e32 v86, v87, v87
	v_fma_f32 v88, -v88, v86, 0.5
	v_fma_f32 v86, v87, v88, v87
	v_pk_mul_f32 v[78:79], v[78:79], v[86:87] op_sel_hi:[1,0]
	v_pk_mul_f32 v[76:77], v[76:77], v[86:87] op_sel_hi:[1,0]
	v_pk_mul_f32 v[74:75], v[74:75], v[86:87] op_sel_hi:[1,0]
	v_pk_mul_f32 v[72:73], v[72:73], v[86:87] op_sel_hi:[1,0]
	v_pk_mul_f32 v[66:67], v[66:67], v[86:87] op_sel_hi:[1,0]
	v_pk_mul_f32 v[64:65], v[64:65], v[86:87] op_sel_hi:[1,0]
	v_pk_mul_f32 v[70:71], v[70:71], v[86:87] op_sel_hi:[1,0]
	v_pk_mul_f32 v[68:69], v[68:69], v[86:87] op_sel_hi:[1,0]
	v_max_f32_e32 v76, 0, v76
	v_max_f32_e32 v72, 0, v72
	v_max_f32_e32 v77, 0, v77
	v_max_f32_e32 v73, 0, v73
	v_max_f32_e32 v78, 0, v78
	v_max_f32_e32 v74, 0, v74
	v_max_f32_e32 v79, 0, v79
	v_max_f32_e32 v75, 0, v75
	v_max_f32_e32 v64, 0, v64
	v_max_f32_e32 v65, 0, v65
	v_max_f32_e32 v66, 0, v66
	v_max_f32_e32 v67, 0, v67
	v_max_f32_e32 v68, 0, v68
	v_max_f32_e32 v69, 0, v69
	v_max_f32_e32 v70, 0, v70
	v_max_f32_e32 v71, 0, v71
	v_mul_f32_e32 v76, v76, v76
	v_mul_f32_e32 v72, v72, v72
	v_mul_f32_e32 v77, v77, v77
	v_mul_f32_e32 v73, v73, v73
	v_mul_f32_e32 v78, v78, v78
	v_mul_f32_e32 v74, v74, v74
	v_mul_f32_e32 v79, v79, v79
	v_mul_f32_e32 v75, v75, v75
	v_mul_f32_e32 v86, v64, v64
	v_mul_f32_e32 v87, v65, v65
	v_mul_f32_e32 v88, v66, v66
	v_mul_f32_e32 v89, v67, v67
	v_cvt_pk_bf16_f32 v64, v76, v77
	v_cvt_pk_bf16_f32 v65, v78, v79
	v_cvt_pk_bf16_f32 v66, v72, v73
	v_cvt_pk_bf16_f32 v67, v74, v75
	v_mul_f32_e32 v68, v68, v68
	v_mul_f32_e32 v69, v69, v69
	v_mul_f32_e32 v70, v70, v70
	v_mul_f32_e32 v71, v71, v71
	global_store_dwordx4 v[82:83], v[64:67], off
	s_nop 1
	v_cvt_pk_bf16_f32 v64, v68, v69
	v_cvt_pk_bf16_f32 v65, v70, v71
	v_cvt_pk_bf16_f32 v66, v86, v87
	v_cvt_pk_bf16_f32 v67, v88, v89
	global_store_dwordx4 v[82:83], v[64:67], off offset:64
	s_waitcnt vmcnt(11)
	s_nop 1
	v_mov_b32_e32 v64, v218
	v_mov_b32_e32 v65, v219
	v_mov_b32_e32 v66, v220
	v_mov_b32_e32 v67, v221
	v_mov_b32_e32 v68, v65
	v_mov_b32_e32 v69, v66
	v_mov_b32_e32 v65, v67
	v_pk_add_f32 v[64:65], v[68:69], v[64:65]
	v_lshlrev_b64 v[66:67], 9, v[80:81]
	v_add_f32_e32 v64, v64, v65
	ds_bpermute_b32 v65, v159, v64
	v_lshl_add_u64 v[66:67], s[10:11], 0, v[66:67]
	v_lshl_add_u64 v[66:67], v[66:67], 0, v[146:147]
	s_waitcnt lgkmcnt(0)
	v_add_f32_e32 v68, v64, v65
	ds_bpermute_b32 v69, v160, v68
	v_add_u32_e32 v64, 0x90, v148
	v_ashrrev_i32_e32 v65, 31, v64
	s_waitcnt lgkmcnt(0)
	v_add_f32_e32 v68, v68, v69
	v_fmamk_f32 v68, v68, 0x3a800000, v157
	v_mov_b32_e32 v70, v68
	v_lshlrev_b64 v[68:69], 6, v[64:65]
	v_lshl_add_u64 v[68:69], v[136:137], 0, v[68:69]
	v_rsq_f32_e32 v71, v70
	v_mul_f32_e32 v72, 0.5, v70
	v_mul_f32_e32 v70, v71, v71
	v_fma_f32 v72, -v72, v70, 0.5
	v_fma_f32 v70, v71, v72, v71
	v_pk_mul_f32 v[62:63], v[62:63], v[70:71] op_sel_hi:[1,0]
	v_pk_mul_f32 v[60:61], v[60:61], v[70:71] op_sel_hi:[1,0]
	v_pk_mul_f32 v[58:59], v[58:59], v[70:71] op_sel_hi:[1,0]
	v_pk_mul_f32 v[56:57], v[56:57], v[70:71] op_sel_hi:[1,0]
	v_pk_mul_f32 v[50:51], v[50:51], v[70:71] op_sel_hi:[1,0]
	v_pk_mul_f32 v[48:49], v[48:49], v[70:71] op_sel_hi:[1,0]
	v_pk_mul_f32 v[54:55], v[54:55], v[70:71] op_sel_hi:[1,0]
	v_pk_mul_f32 v[52:53], v[52:53], v[70:71] op_sel_hi:[1,0]
	v_max_f32_e32 v60, 0, v60
	v_max_f32_e32 v56, 0, v56
	v_max_f32_e32 v61, 0, v61
	v_max_f32_e32 v57, 0, v57
	v_max_f32_e32 v62, 0, v62
	v_max_f32_e32 v58, 0, v58
	v_max_f32_e32 v63, 0, v63
	v_max_f32_e32 v59, 0, v59
	v_max_f32_e32 v48, 0, v48
	v_max_f32_e32 v49, 0, v49
	v_max_f32_e32 v50, 0, v50
	v_max_f32_e32 v51, 0, v51
	v_max_f32_e32 v52, 0, v52
	v_max_f32_e32 v53, 0, v53
	v_max_f32_e32 v54, 0, v54
	v_max_f32_e32 v55, 0, v55
	v_mul_f32_e32 v60, v60, v60
	v_mul_f32_e32 v56, v56, v56
	v_mul_f32_e32 v61, v61, v61
	v_mul_f32_e32 v57, v57, v57
	v_mul_f32_e32 v62, v62, v62
	v_mul_f32_e32 v58, v58, v58
	v_mul_f32_e32 v63, v63, v63
	v_mul_f32_e32 v59, v59, v59
	v_mul_f32_e32 v70, v48, v48
	v_mul_f32_e32 v71, v49, v49
	v_mul_f32_e32 v72, v50, v50
	v_mul_f32_e32 v73, v51, v51
	v_cvt_pk_bf16_f32 v48, v60, v61
	v_cvt_pk_bf16_f32 v49, v62, v63
	v_cvt_pk_bf16_f32 v50, v56, v57
	v_cvt_pk_bf16_f32 v51, v58, v59
	v_mul_f32_e32 v52, v52, v52
	v_mul_f32_e32 v53, v53, v53
	v_mul_f32_e32 v54, v54, v54
	v_mul_f32_e32 v55, v55, v55
	global_store_dwordx4 v[66:67], v[48:51], off
	s_nop 1
	v_cvt_pk_bf16_f32 v48, v52, v53
	v_cvt_pk_bf16_f32 v49, v54, v55
	v_cvt_pk_bf16_f32 v50, v70, v71
	v_cvt_pk_bf16_f32 v51, v72, v73
	global_store_dwordx4 v[66:67], v[48:51], off offset:64
	s_waitcnt vmcnt(12)
	s_nop 1
	v_mov_b32_e32 v48, v222
	v_mov_b32_e32 v49, v223
	v_mov_b32_e32 v50, v224
	v_mov_b32_e32 v51, v225
	v_mov_b32_e32 v52, v49
	v_mov_b32_e32 v53, v50
	v_mov_b32_e32 v49, v51
	v_pk_add_f32 v[48:49], v[52:53], v[48:49]
	v_lshlrev_b64 v[50:51], 9, v[64:65]
	v_add_f32_e32 v48, v48, v49
	ds_bpermute_b32 v49, v159, v48
	v_lshl_add_u64 v[50:51], s[10:11], 0, v[50:51]
	v_lshl_add_u64 v[50:51], v[50:51], 0, v[146:147]
	s_waitcnt lgkmcnt(0)
	v_add_f32_e32 v52, v48, v49
	ds_bpermute_b32 v53, v160, v52
	v_add_u32_e32 v48, 0xa0, v148
	v_ashrrev_i32_e32 v49, 31, v48
	s_waitcnt lgkmcnt(0)
	v_add_f32_e32 v52, v52, v53
	v_fmamk_f32 v52, v52, 0x3a800000, v157
	v_mov_b32_e32 v54, v52
	v_lshlrev_b64 v[52:53], 6, v[48:49]
	v_lshl_add_u64 v[52:53], v[136:137], 0, v[52:53]
	v_rsq_f32_e32 v55, v54
	v_mul_f32_e32 v56, 0.5, v54
	v_mul_f32_e32 v54, v55, v55
	v_fma_f32 v56, -v56, v54, 0.5
	v_fma_f32 v54, v55, v56, v55
	v_pk_mul_f32 v[46:47], v[46:47], v[54:55] op_sel_hi:[1,0]
	v_pk_mul_f32 v[44:45], v[44:45], v[54:55] op_sel_hi:[1,0]
	v_pk_mul_f32 v[42:43], v[42:43], v[54:55] op_sel_hi:[1,0]
	v_pk_mul_f32 v[40:41], v[40:41], v[54:55] op_sel_hi:[1,0]
	v_pk_mul_f32 v[34:35], v[34:35], v[54:55] op_sel_hi:[1,0]
	v_pk_mul_f32 v[32:33], v[32:33], v[54:55] op_sel_hi:[1,0]
	v_pk_mul_f32 v[38:39], v[38:39], v[54:55] op_sel_hi:[1,0]
	v_pk_mul_f32 v[36:37], v[36:37], v[54:55] op_sel_hi:[1,0]
	v_max_f32_e32 v44, 0, v44
	v_max_f32_e32 v40, 0, v40
	v_max_f32_e32 v45, 0, v45
	v_max_f32_e32 v41, 0, v41
	v_max_f32_e32 v46, 0, v46
	v_max_f32_e32 v42, 0, v42
	v_max_f32_e32 v47, 0, v47
	v_max_f32_e32 v43, 0, v43
	v_max_f32_e32 v32, 0, v32
	v_max_f32_e32 v33, 0, v33
	v_max_f32_e32 v34, 0, v34
	v_max_f32_e32 v35, 0, v35
	v_max_f32_e32 v36, 0, v36
	v_max_f32_e32 v37, 0, v37
	v_max_f32_e32 v38, 0, v38
	v_max_f32_e32 v39, 0, v39
	v_mul_f32_e32 v44, v44, v44
	v_mul_f32_e32 v40, v40, v40
	v_mul_f32_e32 v45, v45, v45
	v_mul_f32_e32 v41, v41, v41
	v_mul_f32_e32 v46, v46, v46
	v_mul_f32_e32 v42, v42, v42
	v_mul_f32_e32 v47, v47, v47
	v_mul_f32_e32 v43, v43, v43
	v_mul_f32_e32 v54, v32, v32
	v_mul_f32_e32 v55, v33, v33
	v_mul_f32_e32 v56, v34, v34
	v_mul_f32_e32 v57, v35, v35
	v_cvt_pk_bf16_f32 v32, v44, v45
	v_cvt_pk_bf16_f32 v33, v46, v47
	v_cvt_pk_bf16_f32 v34, v40, v41
	v_cvt_pk_bf16_f32 v35, v42, v43
	v_mul_f32_e32 v36, v36, v36
	v_mul_f32_e32 v37, v37, v37
	v_mul_f32_e32 v38, v38, v38
	v_mul_f32_e32 v39, v39, v39
	global_store_dwordx4 v[50:51], v[32:35], off
	s_nop 1
	v_cvt_pk_bf16_f32 v32, v36, v37
	v_cvt_pk_bf16_f32 v33, v38, v39
	v_cvt_pk_bf16_f32 v34, v54, v55
	v_cvt_pk_bf16_f32 v35, v56, v57
	global_store_dwordx4 v[50:51], v[32:35], off offset:64
	s_waitcnt vmcnt(13)
	s_nop 1
	v_mov_b32_e32 v32, v226
	v_mov_b32_e32 v33, v227
	v_mov_b32_e32 v34, v228
	v_mov_b32_e32 v35, v229
	v_mov_b32_e32 v36, v33
	v_mov_b32_e32 v37, v34
	v_mov_b32_e32 v33, v35
	v_pk_add_f32 v[32:33], v[36:37], v[32:33]
	v_lshlrev_b64 v[34:35], 9, v[48:49]
	v_add_f32_e32 v32, v32, v33
	ds_bpermute_b32 v33, v159, v32
	v_lshl_add_u64 v[34:35], s[10:11], 0, v[34:35]
	v_lshl_add_u64 v[34:35], v[34:35], 0, v[146:147]
	s_waitcnt lgkmcnt(0)
	v_add_f32_e32 v36, v32, v33
	ds_bpermute_b32 v37, v160, v36
	v_add_u32_e32 v32, 0xb0, v148
	v_ashrrev_i32_e32 v33, 31, v32
	s_waitcnt lgkmcnt(0)
	v_add_f32_e32 v36, v36, v37
	v_fmamk_f32 v36, v36, 0x3a800000, v157
	v_mov_b32_e32 v38, v36
	v_lshlrev_b64 v[36:37], 6, v[32:33]
	v_lshl_add_u64 v[36:37], v[136:137], 0, v[36:37]
	v_rsq_f32_e32 v39, v38
	v_mul_f32_e32 v40, 0.5, v38
	v_mul_f32_e32 v38, v39, v39
	v_fma_f32 v40, -v40, v38, 0.5
	v_fma_f32 v38, v39, v40, v39
	v_pk_mul_f32 v[30:31], v[30:31], v[38:39] op_sel_hi:[1,0]
	v_pk_mul_f32 v[28:29], v[28:29], v[38:39] op_sel_hi:[1,0]
	v_pk_mul_f32 v[26:27], v[26:27], v[38:39] op_sel_hi:[1,0]
	v_pk_mul_f32 v[24:25], v[24:25], v[38:39] op_sel_hi:[1,0]
	v_pk_mul_f32 v[18:19], v[18:19], v[38:39] op_sel_hi:[1,0]
	v_pk_mul_f32 v[16:17], v[16:17], v[38:39] op_sel_hi:[1,0]
	v_pk_mul_f32 v[22:23], v[22:23], v[38:39] op_sel_hi:[1,0]
	v_pk_mul_f32 v[20:21], v[20:21], v[38:39] op_sel_hi:[1,0]
	v_max_f32_e32 v28, 0, v28
	v_max_f32_e32 v24, 0, v24
	v_max_f32_e32 v29, 0, v29
	v_max_f32_e32 v25, 0, v25
	v_max_f32_e32 v30, 0, v30
	v_max_f32_e32 v26, 0, v26
	v_max_f32_e32 v31, 0, v31
	v_max_f32_e32 v27, 0, v27
	v_max_f32_e32 v16, 0, v16
	v_max_f32_e32 v17, 0, v17
	v_max_f32_e32 v18, 0, v18
	v_max_f32_e32 v19, 0, v19
	v_max_f32_e32 v20, 0, v20
	v_max_f32_e32 v21, 0, v21
	v_max_f32_e32 v22, 0, v22
	v_max_f32_e32 v23, 0, v23
	v_mul_f32_e32 v28, v28, v28
	v_mul_f32_e32 v24, v24, v24
	v_mul_f32_e32 v29, v29, v29
	v_mul_f32_e32 v25, v25, v25
	v_mul_f32_e32 v30, v30, v30
	v_mul_f32_e32 v26, v26, v26
	v_mul_f32_e32 v31, v31, v31
	v_mul_f32_e32 v27, v27, v27
	v_mul_f32_e32 v38, v16, v16
	v_mul_f32_e32 v39, v17, v17
	v_mul_f32_e32 v40, v18, v18
	v_mul_f32_e32 v41, v19, v19
	v_cvt_pk_bf16_f32 v16, v28, v29
	v_cvt_pk_bf16_f32 v17, v30, v31
	v_cvt_pk_bf16_f32 v18, v24, v25
	v_cvt_pk_bf16_f32 v19, v26, v27
	v_mul_f32_e32 v20, v20, v20
	v_mul_f32_e32 v21, v21, v21
	v_mul_f32_e32 v22, v22, v22
	v_mul_f32_e32 v23, v23, v23
	global_store_dwordx4 v[34:35], v[16:19], off
	s_nop 1
	v_cvt_pk_bf16_f32 v16, v20, v21
	v_cvt_pk_bf16_f32 v17, v22, v23
	v_cvt_pk_bf16_f32 v18, v38, v39
	v_cvt_pk_bf16_f32 v19, v40, v41
	global_store_dwordx4 v[34:35], v[16:19], off offset:64
	s_waitcnt vmcnt(14)
	s_nop 1
	v_mov_b32_e32 v16, v230
	v_mov_b32_e32 v17, v231
	v_mov_b32_e32 v18, v232
	v_mov_b32_e32 v19, v233
	v_mov_b32_e32 v20, v17
	v_mov_b32_e32 v21, v18
	v_mov_b32_e32 v17, v19
	v_pk_add_f32 v[16:17], v[20:21], v[16:17]
	s_nop 0
	v_add_f32_e32 v16, v16, v17
	ds_bpermute_b32 v17, v159, v16
	s_waitcnt lgkmcnt(0)
	v_add_f32_e32 v16, v16, v17
	ds_bpermute_b32 v17, v160, v16
	s_waitcnt lgkmcnt(0)
	v_add_f32_e32 v16, v16, v17
	v_fmamk_f32 v16, v16, 0x3a800000, v157
	v_mov_b32_e32 v18, v16
	v_lshlrev_b64 v[16:17], 9, v[32:33]
	v_lshl_add_u64 v[16:17], s[10:11], 0, v[16:17]
	v_lshl_add_u64 v[16:17], v[16:17], 0, v[146:147]
	v_rsq_f32_e32 v19, v18
	v_mul_f32_e32 v20, 0.5, v18
	v_mul_f32_e32 v18, v19, v19
	v_fma_f32 v20, -v20, v18, 0.5
	v_fma_f32 v18, v19, v20, v19
	v_pk_mul_f32 v[14:15], v[14:15], v[18:19] op_sel_hi:[1,0]
	v_pk_mul_f32 v[12:13], v[12:13], v[18:19] op_sel_hi:[1,0]
	v_pk_mul_f32 v[10:11], v[10:11], v[18:19] op_sel_hi:[1,0]
	v_pk_mul_f32 v[8:9], v[8:9], v[18:19] op_sel_hi:[1,0]
	v_pk_mul_f32 v[2:3], v[2:3], v[18:19] op_sel_hi:[1,0]
	v_pk_mul_f32 v[0:1], v[0:1], v[18:19] op_sel_hi:[1,0]
	v_pk_mul_f32 v[6:7], v[6:7], v[18:19] op_sel_hi:[1,0]
	v_pk_mul_f32 v[4:5], v[4:5], v[18:19] op_sel_hi:[1,0]
	v_max_f32_e32 v12, 0, v12
	v_max_f32_e32 v8, 0, v8
	v_max_f32_e32 v13, 0, v13
	v_max_f32_e32 v9, 0, v9
	v_max_f32_e32 v14, 0, v14
	v_max_f32_e32 v10, 0, v10
	v_max_f32_e32 v15, 0, v15
	v_max_f32_e32 v11, 0, v11
	v_max_f32_e32 v0, 0, v0
	v_max_f32_e32 v1, 0, v1
	v_max_f32_e32 v2, 0, v2
	v_max_f32_e32 v3, 0, v3
	s_andn2_b64 vcc, exec, s[0:1]
	v_max_f32_e32 v4, 0, v4
	v_max_f32_e32 v5, 0, v5
	v_max_f32_e32 v6, 0, v6
	v_max_f32_e32 v7, 0, v7
	v_mul_f32_e32 v12, v12, v12
	v_mul_f32_e32 v8, v8, v8
	v_mul_f32_e32 v13, v13, v13
	v_mul_f32_e32 v9, v9, v9
	v_mul_f32_e32 v14, v14, v14
	v_mul_f32_e32 v10, v10, v10
	v_mul_f32_e32 v15, v15, v15
	v_mul_f32_e32 v11, v11, v11
	v_mul_f32_e32 v18, v0, v0
	v_mul_f32_e32 v19, v1, v1
	v_mul_f32_e32 v20, v2, v2
	v_mul_f32_e32 v21, v3, v3
	v_cvt_pk_bf16_f32 v0, v12, v13
	v_cvt_pk_bf16_f32 v1, v14, v15
	v_cvt_pk_bf16_f32 v2, v8, v9
	v_cvt_pk_bf16_f32 v3, v10, v11
	s_mov_b64 s[0:1], -1
	v_mul_f32_e32 v4, v4, v4
	v_mul_f32_e32 v5, v5, v5
	v_mul_f32_e32 v6, v6, v6
	v_mul_f32_e32 v7, v7, v7
	global_store_dwordx4 v[16:17], v[0:3], off
	s_nop 1
	v_cvt_pk_bf16_f32 v0, v4, v5
	v_cvt_pk_bf16_f32 v1, v6, v7
	v_cvt_pk_bf16_f32 v2, v18, v19
	v_cvt_pk_bf16_f32 v3, v20, v21
	global_store_dwordx4 v[16:17], v[0:3], off offset:64
	s_cbranch_vccnz .LBB0_768
	s_andn2_b64 vcc, exec, s[8:9]
	s_cbranch_vccnz .LBB0_767
	s_barrier
	s_branch .LBB0_767

.LBB0_840:
	s_andn2_b64 vcc, exec, s[0:1]
	s_cbranch_vccnz .LBB0_876
	v_lshrrev_b32_e32 v2, 1, v192
	s_waitcnt lgkmcnt(0)
	v_lshrrev_b32_e32 v3, 5, v192
	v_and_b32_e32 v2, 24, v2
	v_and_b32_e32 v3, 4, v3
	v_bfe_u32 v4, v192, 2, 2
	v_lshlrev_b32_e32 v0, 4, v192
	v_and_b32_e32 v1, 32, v192
	v_bfe_u32 v10, v192, 2, 4
	v_or3_b32 v2, v3, v4, v2
	v_lshrrev_b32_e32 v3, 3, v192
	s_movk_i32 s0, 0x70
	v_bitop3_b32 v8, v0, v1, 48 bitop3:0x6c
	v_and_b32_e32 v9, 64, v192
	v_and_or_b32 v4, v3, s0, v10
	s_movk_i32 s0, 0x60
	v_add_u32_e32 v11, 0x2000, v0
	v_or_b32_e32 v1, v8, v9
	v_and_or_b32 v3, v3, s0, v2
	v_lshrrev_b32_e32 v0, 7, v11
	s_movk_i32 s0, 0xf0
	s_lshr_b32 s1, s20, 6
	v_lshl_or_b32 v130, v3, 13, v1
	v_and_or_b32 v3, v0, s0, v10
	s_movk_i32 s0, 0xe0
	s_ashr_i32 s37, s36, 31
	s_ashr_i32 s9, s8, 31
	v_and_or_b32 v0, v0, s0, v2
	s_lshr_b32 s0, s20, 8
	s_lshl_b32 s3, s1, 10
	s_lshl_b64 s[4:5], s[36:37], 17
	s_lshl_b64 s[12:13], s[8:9], 21
	v_readlane_b32 s14, v254, 23
	v_readlane_b32 s15, v254, 24
	s_add_u32 s40, s14, s12
	s_addc_u32 s41, s15, s13
	s_add_i32 s29, s3, 0
	s_add_i32 m0, s29, 0x10000
	v_lshl_or_b32 v134, v0, 13, v1
	global_load_lds_dwordx4 v130, s[40:41]
	s_add_i32 m0, s29, 0x12000
	s_add_u32 s12, s40, 0x100000
	global_load_lds_dwordx4 v134, s[40:41]
	s_addc_u32 s13, s41, 0
	s_add_i32 m0, s29, 0x14000
	v_lshl_or_b32 v128, v4, 9, v1
	global_load_lds_dwordx4 v130, s[12:13]
	s_add_i32 m0, s29, 0x16000
	s_add_u32 s38, s10, s4
	s_addc_u32 s39, s11, s5
	s_add_i32 s30, s29, 0x2000
	global_load_lds_dwordx4 v134, s[12:13]
	s_mov_b32 m0, s29
	s_add_u32 s4, s38, 0x10000
	v_lshl_or_b32 v132, v3, 9, v1
	global_load_lds_dwordx4 v128, s[38:39]
	s_mov_b32 m0, s30
	s_addc_u32 s5, s39, 0
	s_add_i32 s31, s29, 0x4000
	global_load_lds_dwordx4 v132, s[38:39]
	s_mov_b32 m0, s31
	s_add_i32 s33, s29, 0x6000
	global_load_lds_dwordx4 v128, s[4:5]
	s_mov_b32 m0, s33
	v_mov_b32_e32 v131, 0
	global_load_lds_dwordx4 v132, s[4:5]
	v_mov_b32_e32 v135, v131
	v_mov_b32_e32 v129, v131
	v_mov_b32_e32 v133, v131
	s_cmp_eq_u32 s0, 1
	s_mov_b32 s9, 0
	v_lshl_add_u64 v[6:7], s[40:41], 0, v[130:131]
	v_lshl_add_u64 v[4:5], s[40:41], 0, v[134:135]
	v_lshl_add_u64 v[0:1], s[38:39], 0, v[128:129]
	s_cselect_b64 s[12:13], -1, 0
	s_cmp_lg_u32 s0, 1
	v_lshl_add_u64 v[2:3], s[38:39], 0, v[132:133]
	s_cbranch_scc1 .LBB0_843
	s_barrier
.LBB0_843:
	s_add_u32 s14, s56, 0x600000
	s_mov_b64 s[18:19], 0x80
	s_addc_u32 s15, s57, 0
	s_and_b32 s44, s1, 3
	s_add_i32 m0, s29, 0x18000
	v_lshl_add_u64 v[6:7], v[6:7], 0, s[18:19]
	s_lshl_b32 s1, s0, 13
	s_lshl_b32 s21, s44, 12
	s_ashr_i32 s45, s2, 31
	s_waitcnt vmcnt(2)
	s_barrier
	global_load_lds_dwordx4 v[6:7], off
	v_lshl_add_u64 v[4:5], v[4:5], 0, s[18:19]
	s_add_i32 m0, s29, 0x1a000
	s_add_i32 s46, s29, 0x8000
	s_add_i32 s47, s29, 0xa000
	global_load_lds_dwordx4 v[4:5], off
	v_lshl_add_u64 v[0:1], v[0:1], 0, s[18:19]
	s_mov_b32 m0, s46
	s_add_u32 s4, s40, 0x100080
	global_load_lds_dwordx4 v[0:1], off
	v_lshl_add_u64 v[0:1], v[2:3], 0, s[18:19]
	s_mov_b32 m0, s47
	s_addc_u32 s5, s41, 0
	global_load_lds_dwordx4 v[0:1], off
	s_add_i32 m0, s29, 0x1c000
	v_lshl_add_u64 v[0:1], s[4:5], 0, v[130:131]
	global_load_lds_dwordx4 v[0:1], off
	v_lshl_add_u64 v[0:1], s[4:5], 0, v[134:135]
	s_add_i32 m0, s29, 0x1e000
	v_lshlrev_b32_e32 v4, 2, v192
	global_load_lds_dwordx4 v[0:1], off
	v_bfe_u32 v0, v192, 4, 2
	v_and_b32_e32 v1, 15, v192
	v_lshlrev_b32_e32 v3, 4, v0
	v_lshl_or_b32 v148, s0, 6, v1
	v_lshl_or_b32 v1, v1, 6, v3
	v_and_b32_e32 v4, 32, v4
	v_lshlrev_b32_e32 v5, 6, v192
	s_movk_i32 s0, 0x3c0
	v_lshlrev_b32_e32 v2, 3, v0
	v_bitop3_b32 v1, v1, s1, v4 bitop3:0xde
	v_and_or_b32 v3, v5, s0, v3
	v_cmp_eq_u32_e64 s[0:1], 0, v0
	v_lshlrev_b32_e32 v0, 6, v192
	v_lshl_or_b32 v150, s44, 6, v2
	v_and_b32_e32 v0, 0xe000, v0
	v_lshlrev_b32_e32 v2, 9, v10
	v_or3_b32 v0, v8, v0, v2
	v_add_u32_e32 v136, v0, v9
	v_lshlrev_b32_e32 v0, 2, v11
	v_and_b32_e32 v0, 0x1e000, v0
	s_waitcnt vmcnt(6)
	s_cmpk_lt_u32 s20, 0x100
	v_or3_b32 v0, v8, v0, v2
	v_bitop3_b32 v149, s21, v3, v4 bitop3:0xf6
	s_cselect_b64 s[20:21], -1, 0
	v_add_u32_e32 v138, v0, v9
	s_add_i32 s50, 0, 0x10000
	s_add_i32 s51, 0, 0x14000
	v_mbcnt_lo_u32_b32 v0, -1, 0
	s_ashr_i32 s48, s60, 31
	s_mov_b32 s49, s60
	v_mov_b32_e32 v137, v131
	v_mov_b32_e32 v139, v131
	v_mov_b64_e32 v[140:141], 0x200
	v_mov_b64_e32 v[142:143], 0x1ff
	v_add_u32_e32 v151, s50, v149
	v_add_u32_e32 v152, s51, v149
	v_add_u32_e32 v153, 0, v1
	v_mbcnt_hi_u32_b32 v154, -1, v0
	s_mov_b32 s62, 0
	s_barrier
	s_branch .LBB0_846

.LBB0_852:
	s_ashr_i32 s23, s22, 31
	s_lshl_b64 s[26:27], s[22:23], 17
	s_add_u32 s26, s10, s26
	s_addc_u32 s27, s11, s27
	s_and_b64 s[34:35], s[4:5], exec
	s_cselect_b32 s23, s27, s39
	s_cselect_b32 s37, s26, s38
	s_ashr_i32 s25, s24, 31
	s_lshl_b64 s[34:35], s[24:25], 21
	v_readlane_b32 s42, v254, 23
	v_readlane_b32 s43, v254, 24
	s_add_u32 s34, s42, s34
	s_addc_u32 s35, s43, s35
	s_and_b64 s[42:43], s[4:5], exec
	s_cselect_b32 s25, s35, s41
	s_cselect_b32 s63, s34, s40
	s_add_u32 s38, s38, 0x10080
	s_addc_u32 s39, s39, 0
	s_add_u32 s64, s40, 0x100
	v_mov_b32_e32 v0, 0
	s_addc_u32 s65, s41, 0
	s_mov_b32 s66, -2
	s_waitcnt lgkmcnt(0)
	v_mov_b32_e32 v1, v0
	v_mov_b32_e32 v2, v0
	v_mov_b32_e32 v3, v0
	v_mov_b32_e32 v4, v0
	v_mov_b32_e32 v5, v0
	v_mov_b32_e32 v6, v0
	v_mov_b32_e32 v7, v0
	v_mov_b32_e32 v16, v0
	v_mov_b32_e32 v17, v0
	v_mov_b32_e32 v18, v0
	v_mov_b32_e32 v19, v0
	v_mov_b32_e32 v20, v0
	v_mov_b32_e32 v21, v0
	v_mov_b32_e32 v22, v0
	v_mov_b32_e32 v23, v0
	v_mov_b32_e32 v32, v0
	v_mov_b32_e32 v33, v0
	v_mov_b32_e32 v34, v0
	v_mov_b32_e32 v35, v0
	v_mov_b32_e32 v36, v0
	v_mov_b32_e32 v37, v0
	v_mov_b32_e32 v38, v0
	v_mov_b32_e32 v39, v0
	v_mov_b32_e32 v48, v0
	v_mov_b32_e32 v49, v0
	v_mov_b32_e32 v50, v0
	v_mov_b32_e32 v51, v0
	v_mov_b32_e32 v52, v0
	v_mov_b32_e32 v53, v0
	v_mov_b32_e32 v54, v0
	v_mov_b32_e32 v55, v0
	v_mov_b32_e32 v8, v0
	v_mov_b32_e32 v9, v0
	v_mov_b32_e32 v10, v0
	v_mov_b32_e32 v11, v0
	v_mov_b32_e32 v12, v0
	v_mov_b32_e32 v13, v0
	v_mov_b32_e32 v14, v0
	v_mov_b32_e32 v15, v0
	v_mov_b32_e32 v24, v0
	v_mov_b32_e32 v25, v0
	v_mov_b32_e32 v26, v0
	v_mov_b32_e32 v27, v0
	v_mov_b32_e32 v28, v0
	v_mov_b32_e32 v29, v0
	v_mov_b32_e32 v30, v0
	v_mov_b32_e32 v31, v0
	v_mov_b32_e32 v40, v0
	v_mov_b32_e32 v41, v0
	v_mov_b32_e32 v42, v0
	v_mov_b32_e32 v43, v0
	v_mov_b32_e32 v44, v0
	v_mov_b32_e32 v45, v0
	v_mov_b32_e32 v46, v0
	v_mov_b32_e32 v47, v0
	v_mov_b32_e32 v56, v0
	v_mov_b32_e32 v57, v0
	v_mov_b32_e32 v58, v0
	v_mov_b32_e32 v59, v0
	v_mov_b32_e32 v60, v0
	v_mov_b32_e32 v61, v0
	v_mov_b32_e32 v62, v0
	v_mov_b32_e32 v63, v0
	v_mov_b32_e32 v64, v0
	v_mov_b32_e32 v65, v0
	v_mov_b32_e32 v66, v0
	v_mov_b32_e32 v67, v0
	v_mov_b32_e32 v68, v0
	v_mov_b32_e32 v69, v0
	v_mov_b32_e32 v70, v0
	v_mov_b32_e32 v71, v0
	v_mov_b32_e32 v80, v0
	v_mov_b32_e32 v81, v0
	v_mov_b32_e32 v82, v0
	v_mov_b32_e32 v83, v0
	v_mov_b32_e32 v84, v0
	v_mov_b32_e32 v85, v0
	v_mov_b32_e32 v86, v0
	v_mov_b32_e32 v87, v0
	v_mov_b32_e32 v96, v0
	v_mov_b32_e32 v97, v0
	v_mov_b32_e32 v98, v0
	v_mov_b32_e32 v99, v0
	v_mov_b32_e32 v100, v0
	v_mov_b32_e32 v101, v0
	v_mov_b32_e32 v102, v0
	v_mov_b32_e32 v103, v0
	v_mov_b32_e32 v112, v0
	v_mov_b32_e32 v113, v0
	v_mov_b32_e32 v114, v0
	v_mov_b32_e32 v115, v0
	v_mov_b32_e32 v116, v0
	v_mov_b32_e32 v117, v0
	v_mov_b32_e32 v118, v0
	v_mov_b32_e32 v119, v0
	v_mov_b32_e32 v72, v0
	v_mov_b32_e32 v73, v0
	v_mov_b32_e32 v74, v0
	v_mov_b32_e32 v75, v0
	v_mov_b32_e32 v76, v0
	v_mov_b32_e32 v77, v0
	v_mov_b32_e32 v78, v0
	v_mov_b32_e32 v79, v0
	v_mov_b32_e32 v88, v0
	v_mov_b32_e32 v89, v0
	v_mov_b32_e32 v90, v0
	v_mov_b32_e32 v91, v0
	v_mov_b32_e32 v92, v0
	v_mov_b32_e32 v93, v0
	v_mov_b32_e32 v94, v0
	v_mov_b32_e32 v95, v0
	v_mov_b32_e32 v104, v0
	v_mov_b32_e32 v105, v0
	v_mov_b32_e32 v106, v0
	v_mov_b32_e32 v107, v0
	v_mov_b32_e32 v108, v0
	v_mov_b32_e32 v109, v0
	v_mov_b32_e32 v110, v0
	v_mov_b32_e32 v111, v0
	v_mov_b32_e32 v120, v0
	v_mov_b32_e32 v121, v0
	v_mov_b32_e32 v122, v0
	v_mov_b32_e32 v123, v0
	v_mov_b32_e32 v124, v0
	v_mov_b32_e32 v125, v0
	v_mov_b32_e32 v126, v0
	v_mov_b32_e32 v127, v0
.LBB0_853:
	ds_read_b128 v[144:147], v151
	ds_read_b128 v[156:159], v151 offset:1024
	ds_read_b128 v[160:163], v151 offset:2048
	ds_read_b128 v[164:167], v151 offset:3072
	ds_read_b128 v[168:171], v152
	ds_read_b128 v[172:175], v152 offset:1024
	ds_read_b128 v[176:179], v152 offset:2048
	ds_read_b128 v[180:183], v152 offset:3072
	s_bitcmp1_b32 s66, 1
	s_mov_b32 s98, 0xfefe80
	s_cselect_b32 s98, 0xffff0080, s98
	s_cselect_b32 s99, -1, 0
	s_add_u32 s40, s38, s98
	s_addc_u32 s41, s39, s99
	s_cmp_eq_u32 s66, 60
	s_cselect_b32 s43, s23, s41
	s_cselect_b32 s42, s37, s40
	s_cselect_b32 s41, s25, s65
	s_cselect_b32 s40, s63, s64
	v_lshl_add_u64 v[188:189], s[38:39], 0, v[136:137]
	s_add_i32 m0, s29, 0xc000
	ds_read_b128 v[184:187], v153
	ds_read_b128 v[194:197], v153 offset:1024
	ds_read_b128 v[206:209], v153 offset:2048
	ds_read_b128 v[210:213], v153 offset:3072
	ds_read_b128 v[214:217], v153 offset:4096
	ds_read_b128 v[218:221], v153 offset:5120
	ds_read_b128 v[222:225], v153 offset:6144
	ds_read_b128 v[226:229], v153 offset:7168
	global_load_lds_dwordx4 v[188:189], off
	v_lshl_add_u64 v[188:189], s[38:39], 0, v[138:139]
	s_add_i32 m0, s29, 0xe000
	s_nop 0
	global_load_lds_dwordx4 v[188:189], off
	s_waitcnt vmcnt(8)
	s_waitcnt lgkmcnt(0)
	s_barrier
	s_setprio 1
	s_waitcnt lgkmcnt(0)
	v_mfma_f32_16x16x32_bf16 v[124:127], v[144:147], v[184:187], v[124:127]
	v_mfma_f32_16x16x32_bf16 v[120:123], v[160:163], v[184:187], v[120:123]
	v_mfma_f32_16x16x32_bf16 v[108:111], v[144:147], v[206:209], v[108:111]
	v_mfma_f32_16x16x32_bf16 v[104:107], v[160:163], v[206:209], v[104:107]
	v_mfma_f32_16x16x32_bf16 v[92:95], v[144:147], v[214:217], v[92:95]
	v_mfma_f32_16x16x32_bf16 v[88:91], v[160:163], v[214:217], v[88:91]
	v_mfma_f32_16x16x32_bf16 v[76:79], v[144:147], v[222:225], v[76:79]
	v_mfma_f32_16x16x32_bf16 v[72:75], v[160:163], v[222:225], v[72:75]
	v_mfma_f32_16x16x32_bf16 v[124:127], v[156:159], v[194:197], v[124:127]
	v_mfma_f32_16x16x32_bf16 v[120:123], v[164:167], v[194:197], v[120:123]
	v_mfma_f32_16x16x32_bf16 v[108:111], v[156:159], v[210:213], v[108:111]
	v_mfma_f32_16x16x32_bf16 v[104:107], v[164:167], v[210:213], v[104:107]
	v_mfma_f32_16x16x32_bf16 v[92:95], v[156:159], v[218:221], v[92:95]
	v_mfma_f32_16x16x32_bf16 v[88:91], v[164:167], v[218:221], v[88:91]
	v_mfma_f32_16x16x32_bf16 v[76:79], v[156:159], v[226:229], v[76:79]
	v_mfma_f32_16x16x32_bf16 v[72:75], v[164:167], v[226:229], v[72:75]
	s_setprio 0
	s_setprio 1
	v_mfma_f32_16x16x32_bf16 v[116:119], v[168:171], v[184:187], v[116:119]
	v_mfma_f32_16x16x32_bf16 v[112:115], v[176:179], v[184:187], v[112:115]
	v_mfma_f32_16x16x32_bf16 v[100:103], v[168:171], v[206:209], v[100:103]
	v_mfma_f32_16x16x32_bf16 v[96:99], v[176:179], v[206:209], v[96:99]
	v_mfma_f32_16x16x32_bf16 v[84:87], v[168:171], v[214:217], v[84:87]
	v_mfma_f32_16x16x32_bf16 v[80:83], v[176:179], v[214:217], v[80:83]
	v_mfma_f32_16x16x32_bf16 v[68:71], v[168:171], v[222:225], v[68:71]
	v_mfma_f32_16x16x32_bf16 v[64:67], v[176:179], v[222:225], v[64:67]
	v_mfma_f32_16x16x32_bf16 v[116:119], v[172:175], v[194:197], v[116:119]
	v_mfma_f32_16x16x32_bf16 v[112:115], v[180:183], v[194:197], v[112:115]
	v_mfma_f32_16x16x32_bf16 v[100:103], v[172:175], v[210:213], v[100:103]
	v_mfma_f32_16x16x32_bf16 v[96:99], v[180:183], v[210:213], v[96:99]
	v_mfma_f32_16x16x32_bf16 v[84:87], v[172:175], v[218:221], v[84:87]
	v_mfma_f32_16x16x32_bf16 v[80:83], v[180:183], v[218:221], v[80:83]
	v_mfma_f32_16x16x32_bf16 v[68:71], v[172:175], v[226:229], v[68:71]
	v_mfma_f32_16x16x32_bf16 v[64:67], v[180:183], v[226:229], v[64:67]
	s_setprio 0
	s_barrier
	s_add_i32 s67, s50, s3
	v_lshl_add_u64 v[188:189], s[40:41], 0, v[130:131]
	s_mov_b32 m0, s67
	ds_read_b128 v[184:187], v153 offset:16384
	ds_read_b128 v[194:197], v153 offset:17408
	ds_read_b128 v[206:209], v153 offset:18432
	ds_read_b128 v[210:213], v153 offset:19456
	ds_read_b128 v[214:217], v153 offset:20480
	ds_read_b128 v[218:221], v153 offset:21504
	ds_read_b128 v[222:225], v153 offset:22528
	ds_read_b128 v[226:229], v153 offset:23552
	global_load_lds_dwordx4 v[188:189], off
	s_add_i32 m0, s67, 0x2000
	s_add_u32 s68, s40, 0x100000
	v_lshl_add_u64 v[230:231], s[40:41], 0, v[134:135]
	s_addc_u32 s69, s41, 0
	s_add_i32 s67, s51, s3
	global_load_lds_dwordx4 v[230:231], off
	v_lshl_add_u64 v[232:233], s[68:69], 0, v[130:131]
	s_mov_b32 m0, s67
	v_lshl_add_u64 v[234:235], s[42:43], 0, v[132:133]
	global_load_lds_dwordx4 v[232:233], off
	v_lshl_add_u64 v[232:233], s[68:69], 0, v[134:135]
	s_add_i32 m0, s67, 0x2000
	s_nop 0
	global_load_lds_dwordx4 v[232:233], off
	v_lshl_add_u64 v[232:233], s[42:43], 0, v[128:129]
	s_mov_b32 m0, s29
	s_nop 0
	global_load_lds_dwordx4 v[232:233], off
	s_mov_b32 m0, s30
	s_nop 0
	global_load_lds_dwordx4 v[234:235], off
	s_waitcnt vmcnt(8)
	s_waitcnt lgkmcnt(0)
	s_barrier
	s_setprio 1
	s_waitcnt lgkmcnt(0)
	v_mfma_f32_16x16x32_bf16 v[60:63], v[144:147], v[184:187], v[60:63]
	v_mfma_f32_16x16x32_bf16 v[56:59], v[160:163], v[184:187], v[56:59]
	v_mfma_f32_16x16x32_bf16 v[44:47], v[144:147], v[206:209], v[44:47]
	v_mfma_f32_16x16x32_bf16 v[40:43], v[160:163], v[206:209], v[40:43]
	v_mfma_f32_16x16x32_bf16 v[28:31], v[144:147], v[214:217], v[28:31]
	v_mfma_f32_16x16x32_bf16 v[24:27], v[160:163], v[214:217], v[24:27]
	v_mfma_f32_16x16x32_bf16 v[12:15], v[144:147], v[222:225], v[12:15]
	v_mfma_f32_16x16x32_bf16 v[8:11], v[160:163], v[222:225], v[8:11]
	v_mfma_f32_16x16x32_bf16 v[60:63], v[156:159], v[194:197], v[60:63]
	v_mfma_f32_16x16x32_bf16 v[56:59], v[164:167], v[194:197], v[56:59]
	v_mfma_f32_16x16x32_bf16 v[44:47], v[156:159], v[210:213], v[44:47]
	v_mfma_f32_16x16x32_bf16 v[40:43], v[164:167], v[210:213], v[40:43]
	v_mfma_f32_16x16x32_bf16 v[28:31], v[156:159], v[218:221], v[28:31]
	v_mfma_f32_16x16x32_bf16 v[24:27], v[164:167], v[218:221], v[24:27]
	v_mfma_f32_16x16x32_bf16 v[12:15], v[156:159], v[226:229], v[12:15]
	v_mfma_f32_16x16x32_bf16 v[8:11], v[164:167], v[226:229], v[8:11]
	s_setprio 0
	s_setprio 1
	v_mfma_f32_16x16x32_bf16 v[52:55], v[168:171], v[184:187], v[52:55]
	v_mfma_f32_16x16x32_bf16 v[48:51], v[176:179], v[184:187], v[48:51]
	v_mfma_f32_16x16x32_bf16 v[36:39], v[168:171], v[206:209], v[36:39]
	v_mfma_f32_16x16x32_bf16 v[32:35], v[176:179], v[206:209], v[32:35]
	v_mfma_f32_16x16x32_bf16 v[20:23], v[168:171], v[214:217], v[20:23]
	v_mfma_f32_16x16x32_bf16 v[16:19], v[176:179], v[214:217], v[16:19]
	v_mfma_f32_16x16x32_bf16 v[4:7], v[168:171], v[222:225], v[4:7]
	v_mfma_f32_16x16x32_bf16 v[0:3], v[176:179], v[222:225], v[0:3]
	v_mfma_f32_16x16x32_bf16 v[52:55], v[172:175], v[194:197], v[52:55]
	v_mfma_f32_16x16x32_bf16 v[48:51], v[180:183], v[194:197], v[48:51]
	v_mfma_f32_16x16x32_bf16 v[36:39], v[172:175], v[210:213], v[36:39]
	v_mfma_f32_16x16x32_bf16 v[32:35], v[180:183], v[210:213], v[32:35]
	v_mfma_f32_16x16x32_bf16 v[20:23], v[172:175], v[218:221], v[20:23]
	v_mfma_f32_16x16x32_bf16 v[16:19], v[180:183], v[218:221], v[16:19]
	v_mfma_f32_16x16x32_bf16 v[4:7], v[172:175], v[226:229], v[4:7]
	v_mfma_f32_16x16x32_bf16 v[0:3], v[180:183], v[226:229], v[0:3]
	s_setprio 0
	s_barrier
	s_add_i32 s67, 0, 0x18000
	v_add_u32_e32 v155, s67, v149
	s_add_i32 s68, 0, 0x1c000
	ds_read_b128 v[144:147], v155
	ds_read_b128 v[156:159], v155 offset:1024
	ds_read_b128 v[160:163], v155 offset:2048
	ds_read_b128 v[164:167], v155 offset:3072
	v_add_u32_e32 v155, s68, v149
	ds_read_b128 v[168:171], v155
	ds_read_b128 v[172:175], v155 offset:1024
	ds_read_b128 v[176:179], v155 offset:2048
	ds_read_b128 v[180:183], v155 offset:3072
	s_add_u32 s42, s42, 0x10000
	s_addc_u32 s43, s43, 0
	s_mov_b32 m0, s31
	v_lshl_add_u64 v[236:237], s[42:43], 0, v[128:129]
	ds_read_b128 v[184:187], v153 offset:32768
	ds_read_b128 v[194:197], v153 offset:33792
	ds_read_b128 v[206:209], v153 offset:34816
	ds_read_b128 v[210:213], v153 offset:35840
	ds_read_b128 v[214:217], v153 offset:36864
	ds_read_b128 v[218:221], v153 offset:37888
	ds_read_b128 v[222:225], v153 offset:38912
	ds_read_b128 v[226:229], v153 offset:39936
	global_load_lds_dwordx4 v[236:237], off
	v_lshl_add_u64 v[236:237], s[42:43], 0, v[132:133]
	s_mov_b32 m0, s33
	s_nop 0
	global_load_lds_dwordx4 v[236:237], off
	s_waitcnt vmcnt(8)
	s_waitcnt lgkmcnt(0)
	s_barrier
	s_setprio 1
	s_waitcnt lgkmcnt(0)
	v_mfma_f32_16x16x32_bf16 v[124:127], v[144:147], v[184:187], v[124:127]
	v_mfma_f32_16x16x32_bf16 v[120:123], v[160:163], v[184:187], v[120:123]
	v_mfma_f32_16x16x32_bf16 v[108:111], v[144:147], v[206:209], v[108:111]
	v_mfma_f32_16x16x32_bf16 v[104:107], v[160:163], v[206:209], v[104:107]
	v_mfma_f32_16x16x32_bf16 v[92:95], v[144:147], v[214:217], v[92:95]
	v_mfma_f32_16x16x32_bf16 v[88:91], v[160:163], v[214:217], v[88:91]
	v_mfma_f32_16x16x32_bf16 v[76:79], v[144:147], v[222:225], v[76:79]
	v_mfma_f32_16x16x32_bf16 v[72:75], v[160:163], v[222:225], v[72:75]
	v_mfma_f32_16x16x32_bf16 v[124:127], v[156:159], v[194:197], v[124:127]
	v_mfma_f32_16x16x32_bf16 v[120:123], v[164:167], v[194:197], v[120:123]
	v_mfma_f32_16x16x32_bf16 v[108:111], v[156:159], v[210:213], v[108:111]
	v_mfma_f32_16x16x32_bf16 v[104:107], v[164:167], v[210:213], v[104:107]
	v_mfma_f32_16x16x32_bf16 v[92:95], v[156:159], v[218:221], v[92:95]
	v_mfma_f32_16x16x32_bf16 v[88:91], v[164:167], v[218:221], v[88:91]
	v_mfma_f32_16x16x32_bf16 v[76:79], v[156:159], v[226:229], v[76:79]
	v_mfma_f32_16x16x32_bf16 v[72:75], v[164:167], v[226:229], v[72:75]
	s_setprio 0
	s_setprio 1
	v_mfma_f32_16x16x32_bf16 v[116:119], v[168:171], v[184:187], v[116:119]
	v_mfma_f32_16x16x32_bf16 v[112:115], v[176:179], v[184:187], v[112:115]
	v_mfma_f32_16x16x32_bf16 v[100:103], v[168:171], v[206:209], v[100:103]
	v_mfma_f32_16x16x32_bf16 v[96:99], v[176:179], v[206:209], v[96:99]
	v_mfma_f32_16x16x32_bf16 v[84:87], v[168:171], v[214:217], v[84:87]
	v_mfma_f32_16x16x32_bf16 v[80:83], v[176:179], v[214:217], v[80:83]
	v_mfma_f32_16x16x32_bf16 v[68:71], v[168:171], v[222:225], v[68:71]
	v_mfma_f32_16x16x32_bf16 v[64:67], v[176:179], v[222:225], v[64:67]
	v_mfma_f32_16x16x32_bf16 v[116:119], v[172:175], v[194:197], v[116:119]
	v_mfma_f32_16x16x32_bf16 v[112:115], v[180:183], v[194:197], v[112:115]
	v_mfma_f32_16x16x32_bf16 v[100:103], v[172:175], v[210:213], v[100:103]
	v_mfma_f32_16x16x32_bf16 v[96:99], v[180:183], v[210:213], v[96:99]
	v_mfma_f32_16x16x32_bf16 v[84:87], v[172:175], v[218:221], v[84:87]
	v_mfma_f32_16x16x32_bf16 v[80:83], v[180:183], v[218:221], v[80:83]
	v_mfma_f32_16x16x32_bf16 v[68:71], v[172:175], v[226:229], v[68:71]
	v_mfma_f32_16x16x32_bf16 v[64:67], v[180:183], v[226:229], v[64:67]
	s_setprio 0
	s_barrier
	s_add_i32 s42, s67, s3
	v_lshl_add_u64 v[188:189], v[188:189], 0, s[18:19]
	s_mov_b32 m0, s42
	ds_read_b128 v[184:187], v153 offset:49152
	ds_read_b128 v[194:197], v153 offset:50176
	ds_read_b128 v[206:209], v153 offset:51200
	ds_read_b128 v[210:213], v153 offset:52224
	ds_read_b128 v[214:217], v153 offset:53248
	ds_read_b128 v[218:221], v153 offset:54272
	ds_read_b128 v[222:225], v153 offset:55296
	ds_read_b128 v[226:229], v153 offset:56320
	global_load_lds_dwordx4 v[188:189], off
	s_add_i32 m0, s42, 0x2000
	s_add_u32 s40, s40, 0x100080
	v_lshl_add_u64 v[188:189], v[230:231], 0, s[18:19]
	s_addc_u32 s41, s41, 0
	s_add_i32 s42, s68, s3
	global_load_lds_dwordx4 v[188:189], off
	v_lshl_add_u64 v[188:189], s[40:41], 0, v[130:131]
	s_mov_b32 m0, s42
	s_nop 0
	global_load_lds_dwordx4 v[188:189], off
	v_lshl_add_u64 v[188:189], s[40:41], 0, v[134:135]
	s_add_i32 m0, s42, 0x2000
	s_nop 0
	global_load_lds_dwordx4 v[188:189], off
	v_lshl_add_u64 v[188:189], v[232:233], 0, s[18:19]
	s_mov_b32 m0, s46
	s_nop 0
	global_load_lds_dwordx4 v[188:189], off
	v_lshl_add_u64 v[188:189], v[234:235], 0, s[18:19]
	s_mov_b32 m0, s47
	s_nop 0
	global_load_lds_dwordx4 v[188:189], off
	s_waitcnt vmcnt(8)
	s_waitcnt lgkmcnt(0)
	s_barrier
	s_setprio 1
	s_waitcnt lgkmcnt(0)
	v_mfma_f32_16x16x32_bf16 v[60:63], v[144:147], v[184:187], v[60:63]
	v_mfma_f32_16x16x32_bf16 v[56:59], v[160:163], v[184:187], v[56:59]
	v_mfma_f32_16x16x32_bf16 v[44:47], v[144:147], v[206:209], v[44:47]
	v_mfma_f32_16x16x32_bf16 v[40:43], v[160:163], v[206:209], v[40:43]
	v_mfma_f32_16x16x32_bf16 v[28:31], v[144:147], v[214:217], v[28:31]
	v_mfma_f32_16x16x32_bf16 v[24:27], v[160:163], v[214:217], v[24:27]
	v_mfma_f32_16x16x32_bf16 v[12:15], v[144:147], v[222:225], v[12:15]
	v_mfma_f32_16x16x32_bf16 v[8:11], v[160:163], v[222:225], v[8:11]
	v_mfma_f32_16x16x32_bf16 v[60:63], v[156:159], v[194:197], v[60:63]
	v_mfma_f32_16x16x32_bf16 v[56:59], v[164:167], v[194:197], v[56:59]
	v_mfma_f32_16x16x32_bf16 v[44:47], v[156:159], v[210:213], v[44:47]
	v_mfma_f32_16x16x32_bf16 v[40:43], v[164:167], v[210:213], v[40:43]
	v_mfma_f32_16x16x32_bf16 v[28:31], v[156:159], v[218:221], v[28:31]
	v_mfma_f32_16x16x32_bf16 v[24:27], v[164:167], v[218:221], v[24:27]
	v_mfma_f32_16x16x32_bf16 v[12:15], v[156:159], v[226:229], v[12:15]
	v_mfma_f32_16x16x32_bf16 v[8:11], v[164:167], v[226:229], v[8:11]
	s_setprio 0
	s_setprio 1
	v_mfma_f32_16x16x32_bf16 v[52:55], v[168:171], v[184:187], v[52:55]
	v_mfma_f32_16x16x32_bf16 v[48:51], v[176:179], v[184:187], v[48:51]
	v_mfma_f32_16x16x32_bf16 v[36:39], v[168:171], v[206:209], v[36:39]
	v_mfma_f32_16x16x32_bf16 v[32:35], v[176:179], v[206:209], v[32:35]
	v_mfma_f32_16x16x32_bf16 v[20:23], v[168:171], v[214:217], v[20:23]
	v_mfma_f32_16x16x32_bf16 v[16:19], v[176:179], v[214:217], v[16:19]
	v_mfma_f32_16x16x32_bf16 v[4:7], v[168:171], v[222:225], v[4:7]
	v_mfma_f32_16x16x32_bf16 v[0:3], v[176:179], v[222:225], v[0:3]
	v_mfma_f32_16x16x32_bf16 v[52:55], v[172:175], v[194:197], v[52:55]
	v_mfma_f32_16x16x32_bf16 v[48:51], v[180:183], v[194:197], v[48:51]
	v_mfma_f32_16x16x32_bf16 v[36:39], v[172:175], v[210:213], v[36:39]
	v_mfma_f32_16x16x32_bf16 v[32:35], v[180:183], v[210:213], v[32:35]
	v_mfma_f32_16x16x32_bf16 v[20:23], v[172:175], v[218:221], v[20:23]
	v_mfma_f32_16x16x32_bf16 v[16:19], v[180:183], v[218:221], v[16:19]
	v_mfma_f32_16x16x32_bf16 v[4:7], v[172:175], v[226:229], v[4:7]
	v_mfma_f32_16x16x32_bf16 v[0:3], v[180:183], v[226:229], v[0:3]
	s_setprio 0
	s_barrier
	s_bitcmp1_b32 s66, 1
	s_mov_b32 s98, 0xffff00
	s_cselect_b32 s98, 0x100, s98
	s_add_i32 s66, s66, 2
	s_add_u32 s38, s38, s98
	s_addc_u32 s39, s39, 0
	s_add_u32 s64, s64, 0x100
	s_addc_u32 s65, s65, 0
	s_cmp_gt_u32 s66, 61
	s_cbranch_scc0 .LBB0_853
	s_and_b64 vcc, exec, s[20:21]
	s_cbranch_vccz .LBB0_856
	s_barrier

.LBB0_1252:
	v_lshl_add_u32 v148, s4, 8, v150
	v_ashrrev_i32_e32 v149, 31, v148
	v_lshlrev_b64 v[146:147], 6, v[148:149]
	v_lshl_add_u64 v[146:147], v[136:137], 0, v[146:147]
	s_mov_b64 s[98:99], 0x2000
	global_load_dwordx4 v[160:163], v[146:147], off
	global_load_dwordx4 v[206:209], v[146:147], off offset:1024
	global_load_dwordx4 v[210:213], v[146:147], off offset:2048
	global_load_dwordx4 v[214:217], v[146:147], off offset:3072
	v_lshl_add_u64 v[194:195], v[146:147], 0, s[98:99]
	global_load_dwordx4 v[218:221], v[194:195], off
	global_load_dwordx4 v[222:225], v[194:195], off offset:1024
	global_load_dwordx4 v[226:229], v[194:195], off offset:2048
	global_load_dwordx4 v[230:233], v[194:195], off offset:3072
	v_and_b32_e32 v159, 64, v156
	v_xor_b32_e32 v147, 16, v156
	v_add_u32_e32 v167, 64, v159
	v_cmp_lt_i32_e32 vcc, v147, v167
	v_xor_b32_e32 v166, 32, v156
	v_lshl_or_b32 v146, s5, 23, v152
	v_cndmask_b32_e32 v147, v156, v147, vcc
	v_lshlrev_b32_e32 v159, 2, v147
	v_cmp_lt_i32_e32 vcc, v166, v167
	v_ashrrev_i32_e32 v147, 31, v146
	v_lshlrev_b64 v[146:147], 1, v[146:147]
	s_waitcnt vmcnt(7)
	v_mov_b32_e32 v164, v161
	v_mov_b32_e32 v165, v162
	v_mov_b32_e32 v161, v163
	v_pk_add_f32 v[160:161], v[164:165], v[160:161]
	v_lshlrev_b64 v[164:165], 9, v[148:149]
	v_add_f32_e32 v161, v160, v161
	ds_bpermute_b32 v162, v159, v161
	v_cndmask_b32_e32 v160, v156, v166, vcc
	v_lshlrev_b32_e32 v160, 2, v160
	v_lshl_add_u64 v[164:165], s[10:11], 0, v[164:165]
	v_lshl_add_u64 v[164:165], v[164:165], 0, v[146:147]
	s_waitcnt lgkmcnt(0)
	v_add_f32_e32 v161, v161, v162
	ds_bpermute_b32 v166, v160, v161
	v_or_b32_e32 v162, 16, v148
	v_ashrrev_i32_e32 v163, 31, v162
	s_waitcnt lgkmcnt(0)
	v_add_f32_e32 v149, v161, v166
	v_fmamk_f32 v149, v149, 0x3a800000, v157
	v_lshlrev_b64 v[166:167], 6, v[162:163]
	v_lshl_add_u64 v[166:167], v[136:137], 0, v[166:167]
	v_rsq_f32_e32 v161, v149
	v_mul_f32_e32 v170, 0.5, v149
	v_mul_f32_e32 v168, v161, v161
	v_fma_f32 v170, -v170, v168, 0.5
	v_fma_f32 v168, v161, v170, v161
	v_pk_mul_f32 v[126:127], v[126:127], v[168:169] op_sel_hi:[1,0]
	v_pk_mul_f32 v[124:125], v[124:125], v[168:169] op_sel_hi:[1,0]
	v_pk_mul_f32 v[122:123], v[122:123], v[168:169] op_sel_hi:[1,0]
	v_pk_mul_f32 v[120:121], v[120:121], v[168:169] op_sel_hi:[1,0]
	v_pk_mul_f32 v[114:115], v[114:115], v[168:169] op_sel_hi:[1,0]
	v_pk_mul_f32 v[112:113], v[112:113], v[168:169] op_sel_hi:[1,0]
	v_pk_mul_f32 v[118:119], v[118:119], v[168:169] op_sel_hi:[1,0]
	v_pk_mul_f32 v[116:117], v[116:117], v[168:169] op_sel_hi:[1,0]
	v_max_f32_e32 v124, 0, v124
	v_max_f32_e32 v120, 0, v120
	v_max_f32_e32 v125, 0, v125
	v_max_f32_e32 v121, 0, v121
	v_max_f32_e32 v126, 0, v126
	v_max_f32_e32 v122, 0, v122
	v_max_f32_e32 v127, 0, v127
	v_max_f32_e32 v123, 0, v123
	v_max_f32_e32 v112, 0, v112
	v_max_f32_e32 v113, 0, v113
	v_max_f32_e32 v114, 0, v114
	v_max_f32_e32 v115, 0, v115
	v_max_f32_e32 v116, 0, v116
	v_max_f32_e32 v117, 0, v117
	v_max_f32_e32 v118, 0, v118
	v_max_f32_e32 v119, 0, v119
	v_mul_f32_e32 v124, v124, v124
	v_mul_f32_e32 v120, v120, v120
	v_mul_f32_e32 v125, v125, v125
	v_mul_f32_e32 v121, v121, v121
	v_mul_f32_e32 v126, v126, v126
	v_mul_f32_e32 v122, v122, v122
	v_mul_f32_e32 v127, v127, v127
	v_mul_f32_e32 v123, v123, v123
	v_mul_f32_e32 v149, v112, v112
	v_mul_f32_e32 v161, v113, v113
	v_mul_f32_e32 v168, v114, v114
	v_mul_f32_e32 v169, v115, v115
	v_cvt_pk_bf16_f32 v112, v124, v125
	v_cvt_pk_bf16_f32 v113, v126, v127
	v_cvt_pk_bf16_f32 v114, v120, v121
	v_cvt_pk_bf16_f32 v115, v122, v123
	v_mul_f32_e32 v116, v116, v116
	v_mul_f32_e32 v117, v117, v117
	v_mul_f32_e32 v118, v118, v118
	v_mul_f32_e32 v119, v119, v119
	global_store_dwordx4 v[164:165], v[112:115], off
	s_nop 1
	v_cvt_pk_bf16_f32 v112, v116, v117
	v_cvt_pk_bf16_f32 v113, v118, v119
	v_cvt_pk_bf16_f32 v114, v149, v161
	v_cvt_pk_bf16_f32 v115, v168, v169
	global_store_dwordx4 v[164:165], v[112:115], off offset:64
	s_waitcnt vmcnt(8)
	s_nop 1
	v_mov_b32_e32 v112, v206
	v_mov_b32_e32 v113, v207
	v_mov_b32_e32 v114, v208
	v_mov_b32_e32 v115, v209
	v_mov_b32_e32 v116, v113
	v_mov_b32_e32 v117, v114
	v_mov_b32_e32 v113, v115
	v_pk_add_f32 v[112:113], v[116:117], v[112:113]
	v_lshlrev_b64 v[114:115], 9, v[162:163]
	v_add_f32_e32 v112, v112, v113
	ds_bpermute_b32 v113, v159, v112
	v_lshl_add_u64 v[114:115], s[10:11], 0, v[114:115]
	v_lshl_add_u64 v[114:115], v[114:115], 0, v[146:147]
	s_waitcnt lgkmcnt(0)
	v_add_f32_e32 v116, v112, v113
	ds_bpermute_b32 v117, v160, v116
	v_or_b32_e32 v112, 32, v148
	v_ashrrev_i32_e32 v113, 31, v112
	s_waitcnt lgkmcnt(0)
	v_add_f32_e32 v116, v116, v117
	v_fmamk_f32 v116, v116, 0x3a800000, v157
	v_mov_b32_e32 v118, v116
	v_lshlrev_b64 v[116:117], 6, v[112:113]
	v_lshl_add_u64 v[116:117], v[136:137], 0, v[116:117]
	v_rsq_f32_e32 v119, v118
	v_mul_f32_e32 v120, 0.5, v118
	v_mul_f32_e32 v118, v119, v119
	v_fma_f32 v120, -v120, v118, 0.5
	v_fma_f32 v118, v119, v120, v119
	v_pk_mul_f32 v[110:111], v[110:111], v[118:119] op_sel_hi:[1,0]
	v_pk_mul_f32 v[108:109], v[108:109], v[118:119] op_sel_hi:[1,0]
	v_pk_mul_f32 v[106:107], v[106:107], v[118:119] op_sel_hi:[1,0]
	v_pk_mul_f32 v[104:105], v[104:105], v[118:119] op_sel_hi:[1,0]
	v_pk_mul_f32 v[98:99], v[98:99], v[118:119] op_sel_hi:[1,0]
	v_pk_mul_f32 v[96:97], v[96:97], v[118:119] op_sel_hi:[1,0]
	v_pk_mul_f32 v[102:103], v[102:103], v[118:119] op_sel_hi:[1,0]
	v_pk_mul_f32 v[100:101], v[100:101], v[118:119] op_sel_hi:[1,0]
	v_max_f32_e32 v108, 0, v108
	v_max_f32_e32 v104, 0, v104
	v_max_f32_e32 v109, 0, v109
	v_max_f32_e32 v105, 0, v105
	v_max_f32_e32 v110, 0, v110
	v_max_f32_e32 v106, 0, v106
	v_max_f32_e32 v111, 0, v111
	v_max_f32_e32 v107, 0, v107
	v_max_f32_e32 v96, 0, v96
	v_max_f32_e32 v97, 0, v97
	v_max_f32_e32 v98, 0, v98
	v_max_f32_e32 v99, 0, v99
	v_max_f32_e32 v100, 0, v100
	v_max_f32_e32 v101, 0, v101
	v_max_f32_e32 v102, 0, v102
	v_max_f32_e32 v103, 0, v103
	v_mul_f32_e32 v108, v108, v108
	v_mul_f32_e32 v104, v104, v104
	v_mul_f32_e32 v109, v109, v109
	v_mul_f32_e32 v105, v105, v105
	v_mul_f32_e32 v110, v110, v110
	v_mul_f32_e32 v106, v106, v106
	v_mul_f32_e32 v111, v111, v111
	v_mul_f32_e32 v107, v107, v107
	v_mul_f32_e32 v118, v96, v96
	v_mul_f32_e32 v119, v97, v97
	v_mul_f32_e32 v120, v98, v98
	v_mul_f32_e32 v121, v99, v99
	v_cvt_pk_bf16_f32 v96, v108, v109
	v_cvt_pk_bf16_f32 v97, v110, v111
	v_cvt_pk_bf16_f32 v98, v104, v105
	v_cvt_pk_bf16_f32 v99, v106, v107
	v_mul_f32_e32 v100, v100, v100
	v_mul_f32_e32 v101, v101, v101
	v_mul_f32_e32 v102, v102, v102
	v_mul_f32_e32 v103, v103, v103
	global_store_dwordx4 v[114:115], v[96:99], off
	s_nop 1
	v_cvt_pk_bf16_f32 v96, v100, v101
	v_cvt_pk_bf16_f32 v97, v102, v103
	v_cvt_pk_bf16_f32 v98, v118, v119
	v_cvt_pk_bf16_f32 v99, v120, v121
	global_store_dwordx4 v[114:115], v[96:99], off offset:64
	s_waitcnt vmcnt(9)
	s_nop 1
	v_mov_b32_e32 v96, v210
	v_mov_b32_e32 v97, v211
	v_mov_b32_e32 v98, v212
	v_mov_b32_e32 v99, v213
	v_mov_b32_e32 v100, v97
	v_mov_b32_e32 v101, v98
	v_mov_b32_e32 v97, v99
	v_pk_add_f32 v[96:97], v[100:101], v[96:97]
	v_lshlrev_b64 v[98:99], 9, v[112:113]
	v_add_f32_e32 v96, v96, v97
	ds_bpermute_b32 v97, v159, v96
	v_lshl_add_u64 v[98:99], s[10:11], 0, v[98:99]
	v_lshl_add_u64 v[98:99], v[98:99], 0, v[146:147]
	s_waitcnt lgkmcnt(0)
	v_add_f32_e32 v100, v96, v97
	ds_bpermute_b32 v101, v160, v100
	v_or_b32_e32 v96, 48, v148
	v_ashrrev_i32_e32 v97, 31, v96
	s_waitcnt lgkmcnt(0)
	v_add_f32_e32 v100, v100, v101
	v_fmamk_f32 v100, v100, 0x3a800000, v157
	v_mov_b32_e32 v102, v100
	v_lshlrev_b64 v[100:101], 6, v[96:97]
	v_lshl_add_u64 v[100:101], v[136:137], 0, v[100:101]
	v_rsq_f32_e32 v103, v102
	v_mul_f32_e32 v104, 0.5, v102
	v_mul_f32_e32 v102, v103, v103
	v_fma_f32 v104, -v104, v102, 0.5
	v_fma_f32 v102, v103, v104, v103
	v_pk_mul_f32 v[94:95], v[94:95], v[102:103] op_sel_hi:[1,0]
	v_pk_mul_f32 v[92:93], v[92:93], v[102:103] op_sel_hi:[1,0]
	v_pk_mul_f32 v[90:91], v[90:91], v[102:103] op_sel_hi:[1,0]
	v_pk_mul_f32 v[88:89], v[88:89], v[102:103] op_sel_hi:[1,0]
	v_pk_mul_f32 v[82:83], v[82:83], v[102:103] op_sel_hi:[1,0]
	v_pk_mul_f32 v[80:81], v[80:81], v[102:103] op_sel_hi:[1,0]
	v_pk_mul_f32 v[86:87], v[86:87], v[102:103] op_sel_hi:[1,0]
	v_pk_mul_f32 v[84:85], v[84:85], v[102:103] op_sel_hi:[1,0]
	v_max_f32_e32 v92, 0, v92
	v_max_f32_e32 v88, 0, v88
	v_max_f32_e32 v93, 0, v93
	v_max_f32_e32 v89, 0, v89
	v_max_f32_e32 v94, 0, v94
	v_max_f32_e32 v90, 0, v90
	v_max_f32_e32 v95, 0, v95
	v_max_f32_e32 v91, 0, v91
	v_max_f32_e32 v80, 0, v80
	v_max_f32_e32 v81, 0, v81
	v_max_f32_e32 v82, 0, v82
	v_max_f32_e32 v83, 0, v83
	v_max_f32_e32 v84, 0, v84
	v_max_f32_e32 v85, 0, v85
	v_max_f32_e32 v86, 0, v86
	v_max_f32_e32 v87, 0, v87
	v_mul_f32_e32 v92, v92, v92
	v_mul_f32_e32 v88, v88, v88
	v_mul_f32_e32 v93, v93, v93
	v_mul_f32_e32 v89, v89, v89
	v_mul_f32_e32 v94, v94, v94
	v_mul_f32_e32 v90, v90, v90
	v_mul_f32_e32 v95, v95, v95
	v_mul_f32_e32 v91, v91, v91
	v_mul_f32_e32 v102, v80, v80
	v_mul_f32_e32 v103, v81, v81
	v_mul_f32_e32 v104, v82, v82
	v_mul_f32_e32 v105, v83, v83
	v_cvt_pk_bf16_f32 v80, v92, v93
	v_cvt_pk_bf16_f32 v81, v94, v95
	v_cvt_pk_bf16_f32 v82, v88, v89
	v_cvt_pk_bf16_f32 v83, v90, v91
	v_mul_f32_e32 v84, v84, v84
	v_mul_f32_e32 v85, v85, v85
	v_mul_f32_e32 v86, v86, v86
	v_mul_f32_e32 v87, v87, v87
	global_store_dwordx4 v[98:99], v[80:83], off
	s_nop 1
	v_cvt_pk_bf16_f32 v80, v84, v85
	v_cvt_pk_bf16_f32 v81, v86, v87
	v_cvt_pk_bf16_f32 v82, v102, v103
	v_cvt_pk_bf16_f32 v83, v104, v105
	global_store_dwordx4 v[98:99], v[80:83], off offset:64
	s_waitcnt vmcnt(10)
	s_nop 1
	v_mov_b32_e32 v80, v214
	v_mov_b32_e32 v81, v215
	v_mov_b32_e32 v82, v216
	v_mov_b32_e32 v83, v217
	v_mov_b32_e32 v84, v81
	v_mov_b32_e32 v85, v82
	v_mov_b32_e32 v81, v83
	v_pk_add_f32 v[80:81], v[84:85], v[80:81]
	v_lshlrev_b64 v[82:83], 9, v[96:97]
	v_add_f32_e32 v80, v80, v81
	ds_bpermute_b32 v81, v159, v80
	v_lshl_add_u64 v[82:83], s[10:11], 0, v[82:83]
	v_lshl_add_u64 v[82:83], v[82:83], 0, v[146:147]
	s_waitcnt lgkmcnt(0)
	v_add_f32_e32 v84, v80, v81
	ds_bpermute_b32 v85, v160, v84
	v_add_u32_e32 v80, 0x80, v148
	v_ashrrev_i32_e32 v81, 31, v80
	s_waitcnt lgkmcnt(0)
	v_add_f32_e32 v84, v84, v85
	v_fmamk_f32 v84, v84, 0x3a800000, v157
	v_mov_b32_e32 v86, v84
	v_lshlrev_b64 v[84:85], 6, v[80:81]
	v_lshl_add_u64 v[84:85], v[136:137], 0, v[84:85]
	v_rsq_f32_e32 v87, v86
	v_mul_f32_e32 v88, 0.5, v86
	v_mul_f32_e32 v86, v87, v87
	v_fma_f32 v88, -v88, v86, 0.5
	v_fma_f32 v86, v87, v88, v87
	v_pk_mul_f32 v[78:79], v[78:79], v[86:87] op_sel_hi:[1,0]
	v_pk_mul_f32 v[76:77], v[76:77], v[86:87] op_sel_hi:[1,0]
	v_pk_mul_f32 v[74:75], v[74:75], v[86:87] op_sel_hi:[1,0]
	v_pk_mul_f32 v[72:73], v[72:73], v[86:87] op_sel_hi:[1,0]
	v_pk_mul_f32 v[66:67], v[66:67], v[86:87] op_sel_hi:[1,0]
	v_pk_mul_f32 v[64:65], v[64:65], v[86:87] op_sel_hi:[1,0]
	v_pk_mul_f32 v[70:71], v[70:71], v[86:87] op_sel_hi:[1,0]
	v_pk_mul_f32 v[68:69], v[68:69], v[86:87] op_sel_hi:[1,0]
	v_max_f32_e32 v76, 0, v76
	v_max_f32_e32 v72, 0, v72
	v_max_f32_e32 v77, 0, v77
	v_max_f32_e32 v73, 0, v73
	v_max_f32_e32 v78, 0, v78
	v_max_f32_e32 v74, 0, v74
	v_max_f32_e32 v79, 0, v79
	v_max_f32_e32 v75, 0, v75
	v_max_f32_e32 v64, 0, v64
	v_max_f32_e32 v65, 0, v65
	v_max_f32_e32 v66, 0, v66
	v_max_f32_e32 v67, 0, v67
	v_max_f32_e32 v68, 0, v68
	v_max_f32_e32 v69, 0, v69
	v_max_f32_e32 v70, 0, v70
	v_max_f32_e32 v71, 0, v71
	v_mul_f32_e32 v76, v76, v76
	v_mul_f32_e32 v72, v72, v72
	v_mul_f32_e32 v77, v77, v77
	v_mul_f32_e32 v73, v73, v73
	v_mul_f32_e32 v78, v78, v78
	v_mul_f32_e32 v74, v74, v74
	v_mul_f32_e32 v79, v79, v79
	v_mul_f32_e32 v75, v75, v75
	v_mul_f32_e32 v86, v64, v64
	v_mul_f32_e32 v87, v65, v65
	v_mul_f32_e32 v88, v66, v66
	v_mul_f32_e32 v89, v67, v67
	v_cvt_pk_bf16_f32 v64, v76, v77
	v_cvt_pk_bf16_f32 v65, v78, v79
	v_cvt_pk_bf16_f32 v66, v72, v73
	v_cvt_pk_bf16_f32 v67, v74, v75
	v_mul_f32_e32 v68, v68, v68
	v_mul_f32_e32 v69, v69, v69
	v_mul_f32_e32 v70, v70, v70
	v_mul_f32_e32 v71, v71, v71
	global_store_dwordx4 v[82:83], v[64:67], off
	s_nop 1
	v_cvt_pk_bf16_f32 v64, v68, v69
	v_cvt_pk_bf16_f32 v65, v70, v71
	v_cvt_pk_bf16_f32 v66, v86, v87
	v_cvt_pk_bf16_f32 v67, v88, v89
	global_store_dwordx4 v[82:83], v[64:67], off offset:64
	s_waitcnt vmcnt(11)
	s_nop 1
	v_mov_b32_e32 v64, v218
	v_mov_b32_e32 v65, v219
	v_mov_b32_e32 v66, v220
	v_mov_b32_e32 v67, v221
	v_mov_b32_e32 v68, v65
	v_mov_b32_e32 v69, v66
	v_mov_b32_e32 v65, v67
	v_pk_add_f32 v[64:65], v[68:69], v[64:65]
	v_lshlrev_b64 v[66:67], 9, v[80:81]
	v_add_f32_e32 v64, v64, v65
	ds_bpermute_b32 v65, v159, v64
	v_lshl_add_u64 v[66:67], s[10:11], 0, v[66:67]
	v_lshl_add_u64 v[66:67], v[66:67], 0, v[146:147]
	s_waitcnt lgkmcnt(0)
	v_add_f32_e32 v68, v64, v65
	ds_bpermute_b32 v69, v160, v68
	v_add_u32_e32 v64, 0x90, v148
	v_ashrrev_i32_e32 v65, 31, v64
	s_waitcnt lgkmcnt(0)
	v_add_f32_e32 v68, v68, v69
	v_fmamk_f32 v68, v68, 0x3a800000, v157
	v_mov_b32_e32 v70, v68
	v_lshlrev_b64 v[68:69], 6, v[64:65]
	v_lshl_add_u64 v[68:69], v[136:137], 0, v[68:69]
	v_rsq_f32_e32 v71, v70
	v_mul_f32_e32 v72, 0.5, v70
	v_mul_f32_e32 v70, v71, v71
	v_fma_f32 v72, -v72, v70, 0.5
	v_fma_f32 v70, v71, v72, v71
	v_pk_mul_f32 v[62:63], v[62:63], v[70:71] op_sel_hi:[1,0]
	v_pk_mul_f32 v[60:61], v[60:61], v[70:71] op_sel_hi:[1,0]
	v_pk_mul_f32 v[58:59], v[58:59], v[70:71] op_sel_hi:[1,0]
	v_pk_mul_f32 v[56:57], v[56:57], v[70:71] op_sel_hi:[1,0]
	v_pk_mul_f32 v[50:51], v[50:51], v[70:71] op_sel_hi:[1,0]
	v_pk_mul_f32 v[48:49], v[48:49], v[70:71] op_sel_hi:[1,0]
	v_pk_mul_f32 v[54:55], v[54:55], v[70:71] op_sel_hi:[1,0]
	v_pk_mul_f32 v[52:53], v[52:53], v[70:71] op_sel_hi:[1,0]
	v_max_f32_e32 v60, 0, v60
	v_max_f32_e32 v56, 0, v56
	v_max_f32_e32 v61, 0, v61
	v_max_f32_e32 v57, 0, v57
	v_max_f32_e32 v62, 0, v62
	v_max_f32_e32 v58, 0, v58
	v_max_f32_e32 v63, 0, v63
	v_max_f32_e32 v59, 0, v59
	v_max_f32_e32 v48, 0, v48
	v_max_f32_e32 v49, 0, v49
	v_max_f32_e32 v50, 0, v50
	v_max_f32_e32 v51, 0, v51
	v_max_f32_e32 v52, 0, v52
	v_max_f32_e32 v53, 0, v53
	v_max_f32_e32 v54, 0, v54
	v_max_f32_e32 v55, 0, v55
	v_mul_f32_e32 v60, v60, v60
	v_mul_f32_e32 v56, v56, v56
	v_mul_f32_e32 v61, v61, v61
	v_mul_f32_e32 v57, v57, v57
	v_mul_f32_e32 v62, v62, v62
	v_mul_f32_e32 v58, v58, v58
	v_mul_f32_e32 v63, v63, v63
	v_mul_f32_e32 v59, v59, v59
	v_mul_f32_e32 v70, v48, v48
	v_mul_f32_e32 v71, v49, v49
	v_mul_f32_e32 v72, v50, v50
	v_mul_f32_e32 v73, v51, v51
	v_cvt_pk_bf16_f32 v48, v60, v61
	v_cvt_pk_bf16_f32 v49, v62, v63
	v_cvt_pk_bf16_f32 v50, v56, v57
	v_cvt_pk_bf16_f32 v51, v58, v59
	v_mul_f32_e32 v52, v52, v52
	v_mul_f32_e32 v53, v53, v53
	v_mul_f32_e32 v54, v54, v54
	v_mul_f32_e32 v55, v55, v55
	global_store_dwordx4 v[66:67], v[48:51], off
	s_nop 1
	v_cvt_pk_bf16_f32 v48, v52, v53
	v_cvt_pk_bf16_f32 v49, v54, v55
	v_cvt_pk_bf16_f32 v50, v70, v71
	v_cvt_pk_bf16_f32 v51, v72, v73
	global_store_dwordx4 v[66:67], v[48:51], off offset:64
	s_waitcnt vmcnt(12)
	s_nop 1
	v_mov_b32_e32 v48, v222
	v_mov_b32_e32 v49, v223
	v_mov_b32_e32 v50, v224
	v_mov_b32_e32 v51, v225
	v_mov_b32_e32 v52, v49
	v_mov_b32_e32 v53, v50
	v_mov_b32_e32 v49, v51
	v_pk_add_f32 v[48:49], v[52:53], v[48:49]
	v_lshlrev_b64 v[50:51], 9, v[64:65]
	v_add_f32_e32 v48, v48, v49
	ds_bpermute_b32 v49, v159, v48
	v_lshl_add_u64 v[50:51], s[10:11], 0, v[50:51]
	v_lshl_add_u64 v[50:51], v[50:51], 0, v[146:147]
	s_waitcnt lgkmcnt(0)
	v_add_f32_e32 v52, v48, v49
	ds_bpermute_b32 v53, v160, v52
	v_add_u32_e32 v48, 0xa0, v148
	v_ashrrev_i32_e32 v49, 31, v48
	s_waitcnt lgkmcnt(0)
	v_add_f32_e32 v52, v52, v53
	v_fmamk_f32 v52, v52, 0x3a800000, v157
	v_mov_b32_e32 v54, v52
	v_lshlrev_b64 v[52:53], 6, v[48:49]
	v_lshl_add_u64 v[52:53], v[136:137], 0, v[52:53]
	v_rsq_f32_e32 v55, v54
	v_mul_f32_e32 v56, 0.5, v54
	v_mul_f32_e32 v54, v55, v55
	v_fma_f32 v56, -v56, v54, 0.5
	v_fma_f32 v54, v55, v56, v55
	v_pk_mul_f32 v[46:47], v[46:47], v[54:55] op_sel_hi:[1,0]
	v_pk_mul_f32 v[44:45], v[44:45], v[54:55] op_sel_hi:[1,0]
	v_pk_mul_f32 v[42:43], v[42:43], v[54:55] op_sel_hi:[1,0]
	v_pk_mul_f32 v[40:41], v[40:41], v[54:55] op_sel_hi:[1,0]
	v_pk_mul_f32 v[34:35], v[34:35], v[54:55] op_sel_hi:[1,0]
	v_pk_mul_f32 v[32:33], v[32:33], v[54:55] op_sel_hi:[1,0]
	v_pk_mul_f32 v[38:39], v[38:39], v[54:55] op_sel_hi:[1,0]
	v_pk_mul_f32 v[36:37], v[36:37], v[54:55] op_sel_hi:[1,0]
	v_max_f32_e32 v44, 0, v44
	v_max_f32_e32 v40, 0, v40
	v_max_f32_e32 v45, 0, v45
	v_max_f32_e32 v41, 0, v41
	v_max_f32_e32 v46, 0, v46
	v_max_f32_e32 v42, 0, v42
	v_max_f32_e32 v47, 0, v47
	v_max_f32_e32 v43, 0, v43
	v_max_f32_e32 v32, 0, v32
	v_max_f32_e32 v33, 0, v33
	v_max_f32_e32 v34, 0, v34
	v_max_f32_e32 v35, 0, v35
	v_max_f32_e32 v36, 0, v36
	v_max_f32_e32 v37, 0, v37
	v_max_f32_e32 v38, 0, v38
	v_max_f32_e32 v39, 0, v39
	v_mul_f32_e32 v44, v44, v44
	v_mul_f32_e32 v40, v40, v40
	v_mul_f32_e32 v45, v45, v45
	v_mul_f32_e32 v41, v41, v41
	v_mul_f32_e32 v46, v46, v46
	v_mul_f32_e32 v42, v42, v42
	v_mul_f32_e32 v47, v47, v47
	v_mul_f32_e32 v43, v43, v43
	v_mul_f32_e32 v54, v32, v32
	v_mul_f32_e32 v55, v33, v33
	v_mul_f32_e32 v56, v34, v34
	v_mul_f32_e32 v57, v35, v35
	v_cvt_pk_bf16_f32 v32, v44, v45
	v_cvt_pk_bf16_f32 v33, v46, v47
	v_cvt_pk_bf16_f32 v34, v40, v41
	v_cvt_pk_bf16_f32 v35, v42, v43
	v_mul_f32_e32 v36, v36, v36
	v_mul_f32_e32 v37, v37, v37
	v_mul_f32_e32 v38, v38, v38
	v_mul_f32_e32 v39, v39, v39
	global_store_dwordx4 v[50:51], v[32:35], off
	s_nop 1
	v_cvt_pk_bf16_f32 v32, v36, v37
	v_cvt_pk_bf16_f32 v33, v38, v39
	v_cvt_pk_bf16_f32 v34, v54, v55
	v_cvt_pk_bf16_f32 v35, v56, v57
	global_store_dwordx4 v[50:51], v[32:35], off offset:64
	s_waitcnt vmcnt(13)
	s_nop 1
	v_mov_b32_e32 v32, v226
	v_mov_b32_e32 v33, v227
	v_mov_b32_e32 v34, v228
	v_mov_b32_e32 v35, v229
	v_mov_b32_e32 v36, v33
	v_mov_b32_e32 v37, v34
	v_mov_b32_e32 v33, v35
	v_pk_add_f32 v[32:33], v[36:37], v[32:33]
	v_lshlrev_b64 v[34:35], 9, v[48:49]
	v_add_f32_e32 v32, v32, v33
	ds_bpermute_b32 v33, v159, v32
	v_lshl_add_u64 v[34:35], s[10:11], 0, v[34:35]
	v_lshl_add_u64 v[34:35], v[34:35], 0, v[146:147]
	s_waitcnt lgkmcnt(0)
	v_add_f32_e32 v36, v32, v33
	ds_bpermute_b32 v37, v160, v36
	v_add_u32_e32 v32, 0xb0, v148
	v_ashrrev_i32_e32 v33, 31, v32
	s_waitcnt lgkmcnt(0)
	v_add_f32_e32 v36, v36, v37
	v_fmamk_f32 v36, v36, 0x3a800000, v157
	v_mov_b32_e32 v38, v36
	v_lshlrev_b64 v[36:37], 6, v[32:33]
	v_lshl_add_u64 v[36:37], v[136:137], 0, v[36:37]
	v_rsq_f32_e32 v39, v38
	v_mul_f32_e32 v40, 0.5, v38
	v_mul_f32_e32 v38, v39, v39
	v_fma_f32 v40, -v40, v38, 0.5
	v_fma_f32 v38, v39, v40, v39
	v_pk_mul_f32 v[30:31], v[30:31], v[38:39] op_sel_hi:[1,0]
	v_pk_mul_f32 v[28:29], v[28:29], v[38:39] op_sel_hi:[1,0]
	v_pk_mul_f32 v[26:27], v[26:27], v[38:39] op_sel_hi:[1,0]
	v_pk_mul_f32 v[24:25], v[24:25], v[38:39] op_sel_hi:[1,0]
	v_pk_mul_f32 v[18:19], v[18:19], v[38:39] op_sel_hi:[1,0]
	v_pk_mul_f32 v[16:17], v[16:17], v[38:39] op_sel_hi:[1,0]
	v_pk_mul_f32 v[22:23], v[22:23], v[38:39] op_sel_hi:[1,0]
	v_pk_mul_f32 v[20:21], v[20:21], v[38:39] op_sel_hi:[1,0]
	v_max_f32_e32 v28, 0, v28
	v_max_f32_e32 v24, 0, v24
	v_max_f32_e32 v29, 0, v29
	v_max_f32_e32 v25, 0, v25
	v_max_f32_e32 v30, 0, v30
	v_max_f32_e32 v26, 0, v26
	v_max_f32_e32 v31, 0, v31
	v_max_f32_e32 v27, 0, v27
	v_max_f32_e32 v16, 0, v16
	v_max_f32_e32 v17, 0, v17
	v_max_f32_e32 v18, 0, v18
	v_max_f32_e32 v19, 0, v19
	v_max_f32_e32 v20, 0, v20
	v_max_f32_e32 v21, 0, v21
	v_max_f32_e32 v22, 0, v22
	v_max_f32_e32 v23, 0, v23
	v_mul_f32_e32 v28, v28, v28
	v_mul_f32_e32 v24, v24, v24
	v_mul_f32_e32 v29, v29, v29
	v_mul_f32_e32 v25, v25, v25
	v_mul_f32_e32 v30, v30, v30
	v_mul_f32_e32 v26, v26, v26
	v_mul_f32_e32 v31, v31, v31
	v_mul_f32_e32 v27, v27, v27
	v_mul_f32_e32 v38, v16, v16
	v_mul_f32_e32 v39, v17, v17
	v_mul_f32_e32 v40, v18, v18
	v_mul_f32_e32 v41, v19, v19
	v_cvt_pk_bf16_f32 v16, v28, v29
	v_cvt_pk_bf16_f32 v17, v30, v31
	v_cvt_pk_bf16_f32 v18, v24, v25
	v_cvt_pk_bf16_f32 v19, v26, v27
	v_mul_f32_e32 v20, v20, v20
	v_mul_f32_e32 v21, v21, v21
	v_mul_f32_e32 v22, v22, v22
	v_mul_f32_e32 v23, v23, v23
	global_store_dwordx4 v[34:35], v[16:19], off
	s_nop 1
	v_cvt_pk_bf16_f32 v16, v20, v21
	v_cvt_pk_bf16_f32 v17, v22, v23
	v_cvt_pk_bf16_f32 v18, v38, v39
	v_cvt_pk_bf16_f32 v19, v40, v41
	global_store_dwordx4 v[34:35], v[16:19], off offset:64
	s_waitcnt vmcnt(14)
	s_nop 1
	v_mov_b32_e32 v16, v230
	v_mov_b32_e32 v17, v231
	v_mov_b32_e32 v18, v232
	v_mov_b32_e32 v19, v233
	v_mov_b32_e32 v20, v17
	v_mov_b32_e32 v21, v18
	v_mov_b32_e32 v17, v19
	v_pk_add_f32 v[16:17], v[20:21], v[16:17]
	s_nop 0
	v_add_f32_e32 v16, v16, v17
	ds_bpermute_b32 v17, v159, v16
	s_waitcnt lgkmcnt(0)
	v_add_f32_e32 v16, v16, v17
	ds_bpermute_b32 v17, v160, v16
	s_waitcnt lgkmcnt(0)
	v_add_f32_e32 v16, v16, v17
	v_fmamk_f32 v16, v16, 0x3a800000, v157
	v_mov_b32_e32 v18, v16
	v_lshlrev_b64 v[16:17], 9, v[32:33]
	v_lshl_add_u64 v[16:17], s[10:11], 0, v[16:17]
	v_lshl_add_u64 v[16:17], v[16:17], 0, v[146:147]
	v_rsq_f32_e32 v19, v18
	v_mul_f32_e32 v20, 0.5, v18
	v_mul_f32_e32 v18, v19, v19
	v_fma_f32 v20, -v20, v18, 0.5
	v_fma_f32 v18, v19, v20, v19
	v_pk_mul_f32 v[14:15], v[14:15], v[18:19] op_sel_hi:[1,0]
	v_pk_mul_f32 v[12:13], v[12:13], v[18:19] op_sel_hi:[1,0]
	v_pk_mul_f32 v[10:11], v[10:11], v[18:19] op_sel_hi:[1,0]
	v_pk_mul_f32 v[8:9], v[8:9], v[18:19] op_sel_hi:[1,0]
	v_pk_mul_f32 v[2:3], v[2:3], v[18:19] op_sel_hi:[1,0]
	v_pk_mul_f32 v[0:1], v[0:1], v[18:19] op_sel_hi:[1,0]
	v_pk_mul_f32 v[6:7], v[6:7], v[18:19] op_sel_hi:[1,0]
	v_pk_mul_f32 v[4:5], v[4:5], v[18:19] op_sel_hi:[1,0]
	v_max_f32_e32 v12, 0, v12
	v_max_f32_e32 v8, 0, v8
	v_max_f32_e32 v13, 0, v13
	v_max_f32_e32 v9, 0, v9
	v_max_f32_e32 v14, 0, v14
	v_max_f32_e32 v10, 0, v10
	v_max_f32_e32 v15, 0, v15
	v_max_f32_e32 v11, 0, v11
	v_max_f32_e32 v0, 0, v0
	v_max_f32_e32 v1, 0, v1
	v_max_f32_e32 v2, 0, v2
	v_max_f32_e32 v3, 0, v3
	s_andn2_b64 vcc, exec, s[0:1]
	v_max_f32_e32 v4, 0, v4
	v_max_f32_e32 v5, 0, v5
	v_max_f32_e32 v6, 0, v6
	v_max_f32_e32 v7, 0, v7
	v_mul_f32_e32 v12, v12, v12
	v_mul_f32_e32 v8, v8, v8
	v_mul_f32_e32 v13, v13, v13
	v_mul_f32_e32 v9, v9, v9
	v_mul_f32_e32 v14, v14, v14
	v_mul_f32_e32 v10, v10, v10
	v_mul_f32_e32 v15, v15, v15
	v_mul_f32_e32 v11, v11, v11
	v_mul_f32_e32 v18, v0, v0
	v_mul_f32_e32 v19, v1, v1
	v_mul_f32_e32 v20, v2, v2
	v_mul_f32_e32 v21, v3, v3
	v_cvt_pk_bf16_f32 v0, v12, v13
	v_cvt_pk_bf16_f32 v1, v14, v15
	v_cvt_pk_bf16_f32 v2, v8, v9
	v_cvt_pk_bf16_f32 v3, v10, v11
	s_mov_b64 s[0:1], -1
	v_mul_f32_e32 v4, v4, v4
	v_mul_f32_e32 v5, v5, v5
	v_mul_f32_e32 v6, v6, v6
	v_mul_f32_e32 v7, v7, v7
	global_store_dwordx4 v[16:17], v[0:3], off
	s_nop 1
	v_cvt_pk_bf16_f32 v0, v4, v5
	v_cvt_pk_bf16_f32 v1, v6, v7
	v_cvt_pk_bf16_f32 v2, v18, v19
	v_cvt_pk_bf16_f32 v3, v20, v21
	global_store_dwordx4 v[16:17], v[0:3], off offset:64
	s_cbranch_vccnz .LBB0_1241
	s_andn2_b64 vcc, exec, s[8:9]
	s_cbranch_vccnz .LBB0_1240
	s_barrier
	s_branch .LBB0_1240

.LBB0_1313:
	s_andn2_b64 vcc, exec, s[0:1]
	s_cbranch_vccnz .LBB0_1349
	v_lshrrev_b32_e32 v2, 1, v192
	s_waitcnt lgkmcnt(0)
	v_lshrrev_b32_e32 v3, 5, v192
	v_and_b32_e32 v2, 24, v2
	v_and_b32_e32 v3, 4, v3
	v_bfe_u32 v4, v192, 2, 2
	v_lshlrev_b32_e32 v0, 4, v192
	v_and_b32_e32 v1, 32, v192
	v_bfe_u32 v10, v192, 2, 4
	v_or3_b32 v2, v3, v4, v2
	v_lshrrev_b32_e32 v3, 3, v192
	s_movk_i32 s0, 0x70
	v_bitop3_b32 v8, v0, v1, 48 bitop3:0x6c
	v_and_b32_e32 v9, 64, v192
	v_and_or_b32 v4, v3, s0, v10
	s_movk_i32 s0, 0x60
	v_add_u32_e32 v11, 0x2000, v0
	v_or_b32_e32 v1, v8, v9
	v_and_or_b32 v3, v3, s0, v2
	v_lshrrev_b32_e32 v0, 7, v11
	s_movk_i32 s0, 0xf0
	s_lshr_b32 s1, s20, 6
	v_lshl_or_b32 v130, v3, 13, v1
	v_and_or_b32 v3, v0, s0, v10
	s_movk_i32 s0, 0xe0
	s_ashr_i32 s37, s36, 31
	s_ashr_i32 s9, s8, 31
	v_and_or_b32 v0, v0, s0, v2
	s_lshr_b32 s0, s20, 8
	s_lshl_b32 s3, s1, 10
	s_lshl_b64 s[4:5], s[36:37], 17
	s_lshl_b64 s[12:13], s[8:9], 21
	v_readlane_b32 s14, v254, 31
	v_readlane_b32 s15, v254, 32
	s_add_u32 s40, s14, s12
	s_addc_u32 s41, s15, s13
	s_add_i32 s29, s3, 0
	s_add_i32 m0, s29, 0x10000
	v_lshl_or_b32 v134, v0, 13, v1
	global_load_lds_dwordx4 v130, s[40:41]
	s_add_i32 m0, s29, 0x12000
	s_add_u32 s12, s40, 0x100000
	global_load_lds_dwordx4 v134, s[40:41]
	s_addc_u32 s13, s41, 0
	s_add_i32 m0, s29, 0x14000
	v_lshl_or_b32 v128, v4, 9, v1
	global_load_lds_dwordx4 v130, s[12:13]
	s_add_i32 m0, s29, 0x16000
	s_add_u32 s38, s10, s4
	s_addc_u32 s39, s11, s5
	s_add_i32 s30, s29, 0x2000
	global_load_lds_dwordx4 v134, s[12:13]
	s_mov_b32 m0, s29
	s_add_u32 s4, s38, 0x10000
	v_lshl_or_b32 v132, v3, 9, v1
	global_load_lds_dwordx4 v128, s[38:39]
	s_mov_b32 m0, s30
	s_addc_u32 s5, s39, 0
	s_add_i32 s31, s29, 0x4000
	global_load_lds_dwordx4 v132, s[38:39]
	s_mov_b32 m0, s31
	s_add_i32 s33, s29, 0x6000
	global_load_lds_dwordx4 v128, s[4:5]
	s_mov_b32 m0, s33
	v_mov_b32_e32 v131, 0
	global_load_lds_dwordx4 v132, s[4:5]
	v_mov_b32_e32 v135, v131
	v_mov_b32_e32 v129, v131
	v_mov_b32_e32 v133, v131
	s_cmp_eq_u32 s0, 1
	s_mov_b32 s9, 0
	v_lshl_add_u64 v[6:7], s[40:41], 0, v[130:131]
	v_lshl_add_u64 v[4:5], s[40:41], 0, v[134:135]
	v_lshl_add_u64 v[0:1], s[38:39], 0, v[128:129]
	s_cselect_b64 s[12:13], -1, 0
	s_cmp_lg_u32 s0, 1
	v_lshl_add_u64 v[2:3], s[38:39], 0, v[132:133]
	s_cbranch_scc1 .LBB0_1316
	s_barrier
.LBB0_1316:
	s_add_u32 s14, s56, 0xa00000
	s_mov_b64 s[18:19], 0x80
	s_addc_u32 s15, s57, 0
	s_and_b32 s44, s1, 3
	s_add_i32 m0, s29, 0x18000
	v_lshl_add_u64 v[6:7], v[6:7], 0, s[18:19]
	s_lshl_b32 s1, s0, 13
	s_lshl_b32 s21, s44, 12
	s_ashr_i32 s45, s2, 31
	s_waitcnt vmcnt(2)
	s_barrier
	global_load_lds_dwordx4 v[6:7], off
	v_lshl_add_u64 v[4:5], v[4:5], 0, s[18:19]
	s_add_i32 m0, s29, 0x1a000
	s_add_i32 s46, s29, 0x8000
	s_add_i32 s47, s29, 0xa000
	global_load_lds_dwordx4 v[4:5], off
	v_lshl_add_u64 v[0:1], v[0:1], 0, s[18:19]
	s_mov_b32 m0, s46
	s_add_u32 s4, s40, 0x100080
	global_load_lds_dwordx4 v[0:1], off
	v_lshl_add_u64 v[0:1], v[2:3], 0, s[18:19]
	s_mov_b32 m0, s47
	s_addc_u32 s5, s41, 0
	global_load_lds_dwordx4 v[0:1], off
	s_add_i32 m0, s29, 0x1c000
	v_lshl_add_u64 v[0:1], s[4:5], 0, v[130:131]
	global_load_lds_dwordx4 v[0:1], off
	v_lshl_add_u64 v[0:1], s[4:5], 0, v[134:135]
	s_add_i32 m0, s29, 0x1e000
	v_lshlrev_b32_e32 v4, 2, v192
	global_load_lds_dwordx4 v[0:1], off
	v_bfe_u32 v0, v192, 4, 2
	v_and_b32_e32 v1, 15, v192
	v_lshlrev_b32_e32 v3, 4, v0
	v_lshl_or_b32 v148, s0, 6, v1
	v_lshl_or_b32 v1, v1, 6, v3
	v_and_b32_e32 v4, 32, v4
	v_lshlrev_b32_e32 v5, 6, v192
	s_movk_i32 s0, 0x3c0
	v_lshlrev_b32_e32 v2, 3, v0
	v_bitop3_b32 v1, v1, s1, v4 bitop3:0xde
	v_and_or_b32 v3, v5, s0, v3
	v_cmp_eq_u32_e64 s[0:1], 0, v0
	v_lshlrev_b32_e32 v0, 6, v192
	v_lshl_or_b32 v150, s44, 6, v2
	v_and_b32_e32 v0, 0xe000, v0
	v_lshlrev_b32_e32 v2, 9, v10
	v_or3_b32 v0, v8, v0, v2
	v_add_u32_e32 v136, v0, v9
	v_lshlrev_b32_e32 v0, 2, v11
	v_and_b32_e32 v0, 0x1e000, v0
	s_waitcnt vmcnt(6)
	s_cmpk_lt_u32 s20, 0x100
	v_or3_b32 v0, v8, v0, v2
	v_bitop3_b32 v149, s21, v3, v4 bitop3:0xf6
	s_cselect_b64 s[20:21], -1, 0
	v_add_u32_e32 v138, v0, v9
	s_add_i32 s50, 0, 0x10000
	s_add_i32 s51, 0, 0x14000
	v_mbcnt_lo_u32_b32 v0, -1, 0
	s_ashr_i32 s48, s60, 31
	s_mov_b32 s49, s60
	v_mov_b32_e32 v137, v131
	v_mov_b32_e32 v139, v131
	v_mov_b64_e32 v[140:141], 0x200
	v_mov_b64_e32 v[142:143], 0x1ff
	v_add_u32_e32 v151, s50, v149
	v_add_u32_e32 v152, s51, v149
	v_add_u32_e32 v153, 0, v1
	v_mbcnt_hi_u32_b32 v154, -1, v0
	s_mov_b32 s62, 0
	s_barrier
	s_branch .LBB0_1319

.LBB0_1325:
	s_ashr_i32 s23, s22, 31
	s_lshl_b64 s[26:27], s[22:23], 17
	s_add_u32 s26, s10, s26
	s_addc_u32 s27, s11, s27
	s_and_b64 s[34:35], s[4:5], exec
	s_cselect_b32 s23, s27, s39
	s_cselect_b32 s37, s26, s38
	s_ashr_i32 s25, s24, 31
	s_lshl_b64 s[34:35], s[24:25], 21
	v_readlane_b32 s42, v254, 31
	v_readlane_b32 s43, v254, 32
	s_add_u32 s34, s42, s34
	s_addc_u32 s35, s43, s35
	s_and_b64 s[42:43], s[4:5], exec
	s_cselect_b32 s25, s35, s41
	s_cselect_b32 s63, s34, s40
	s_add_u32 s38, s38, 0x10080
	s_addc_u32 s39, s39, 0
	s_add_u32 s64, s40, 0x100
	v_mov_b32_e32 v0, 0
	s_addc_u32 s65, s41, 0
	s_mov_b32 s66, -2
	s_waitcnt lgkmcnt(0)
	v_mov_b32_e32 v1, v0
	v_mov_b32_e32 v2, v0
	v_mov_b32_e32 v3, v0
	v_mov_b32_e32 v4, v0
	v_mov_b32_e32 v5, v0
	v_mov_b32_e32 v6, v0
	v_mov_b32_e32 v7, v0
	v_mov_b32_e32 v16, v0
	v_mov_b32_e32 v17, v0
	v_mov_b32_e32 v18, v0
	v_mov_b32_e32 v19, v0
	v_mov_b32_e32 v20, v0
	v_mov_b32_e32 v21, v0
	v_mov_b32_e32 v22, v0
	v_mov_b32_e32 v23, v0
	v_mov_b32_e32 v32, v0
	v_mov_b32_e32 v33, v0
	v_mov_b32_e32 v34, v0
	v_mov_b32_e32 v35, v0
	v_mov_b32_e32 v36, v0
	v_mov_b32_e32 v37, v0
	v_mov_b32_e32 v38, v0
	v_mov_b32_e32 v39, v0
	v_mov_b32_e32 v48, v0
	v_mov_b32_e32 v49, v0
	v_mov_b32_e32 v50, v0
	v_mov_b32_e32 v51, v0
	v_mov_b32_e32 v52, v0
	v_mov_b32_e32 v53, v0
	v_mov_b32_e32 v54, v0
	v_mov_b32_e32 v55, v0
	v_mov_b32_e32 v8, v0
	v_mov_b32_e32 v9, v0
	v_mov_b32_e32 v10, v0
	v_mov_b32_e32 v11, v0
	v_mov_b32_e32 v12, v0
	v_mov_b32_e32 v13, v0
	v_mov_b32_e32 v14, v0
	v_mov_b32_e32 v15, v0
	v_mov_b32_e32 v24, v0
	v_mov_b32_e32 v25, v0
	v_mov_b32_e32 v26, v0
	v_mov_b32_e32 v27, v0
	v_mov_b32_e32 v28, v0
	v_mov_b32_e32 v29, v0
	v_mov_b32_e32 v30, v0
	v_mov_b32_e32 v31, v0
	v_mov_b32_e32 v40, v0
	v_mov_b32_e32 v41, v0
	v_mov_b32_e32 v42, v0
	v_mov_b32_e32 v43, v0
	v_mov_b32_e32 v44, v0
	v_mov_b32_e32 v45, v0
	v_mov_b32_e32 v46, v0
	v_mov_b32_e32 v47, v0
	v_mov_b32_e32 v56, v0
	v_mov_b32_e32 v57, v0
	v_mov_b32_e32 v58, v0
	v_mov_b32_e32 v59, v0
	v_mov_b32_e32 v60, v0
	v_mov_b32_e32 v61, v0
	v_mov_b32_e32 v62, v0
	v_mov_b32_e32 v63, v0
	v_mov_b32_e32 v64, v0
	v_mov_b32_e32 v65, v0
	v_mov_b32_e32 v66, v0
	v_mov_b32_e32 v67, v0
	v_mov_b32_e32 v68, v0
	v_mov_b32_e32 v69, v0
	v_mov_b32_e32 v70, v0
	v_mov_b32_e32 v71, v0
	v_mov_b32_e32 v80, v0
	v_mov_b32_e32 v81, v0
	v_mov_b32_e32 v82, v0
	v_mov_b32_e32 v83, v0
	v_mov_b32_e32 v84, v0
	v_mov_b32_e32 v85, v0
	v_mov_b32_e32 v86, v0
	v_mov_b32_e32 v87, v0
	v_mov_b32_e32 v96, v0
	v_mov_b32_e32 v97, v0
	v_mov_b32_e32 v98, v0
	v_mov_b32_e32 v99, v0
	v_mov_b32_e32 v100, v0
	v_mov_b32_e32 v101, v0
	v_mov_b32_e32 v102, v0
	v_mov_b32_e32 v103, v0
	v_mov_b32_e32 v112, v0
	v_mov_b32_e32 v113, v0
	v_mov_b32_e32 v114, v0
	v_mov_b32_e32 v115, v0
	v_mov_b32_e32 v116, v0
	v_mov_b32_e32 v117, v0
	v_mov_b32_e32 v118, v0
	v_mov_b32_e32 v119, v0
	v_mov_b32_e32 v72, v0
	v_mov_b32_e32 v73, v0
	v_mov_b32_e32 v74, v0
	v_mov_b32_e32 v75, v0
	v_mov_b32_e32 v76, v0
	v_mov_b32_e32 v77, v0
	v_mov_b32_e32 v78, v0
	v_mov_b32_e32 v79, v0
	v_mov_b32_e32 v88, v0
	v_mov_b32_e32 v89, v0
	v_mov_b32_e32 v90, v0
	v_mov_b32_e32 v91, v0
	v_mov_b32_e32 v92, v0
	v_mov_b32_e32 v93, v0
	v_mov_b32_e32 v94, v0
	v_mov_b32_e32 v95, v0
	v_mov_b32_e32 v104, v0
	v_mov_b32_e32 v105, v0
	v_mov_b32_e32 v106, v0
	v_mov_b32_e32 v107, v0
	v_mov_b32_e32 v108, v0
	v_mov_b32_e32 v109, v0
	v_mov_b32_e32 v110, v0
	v_mov_b32_e32 v111, v0
	v_mov_b32_e32 v120, v0
	v_mov_b32_e32 v121, v0
	v_mov_b32_e32 v122, v0
	v_mov_b32_e32 v123, v0
	v_mov_b32_e32 v124, v0
	v_mov_b32_e32 v125, v0
	v_mov_b32_e32 v126, v0
	v_mov_b32_e32 v127, v0
.LBB0_1326:
	ds_read_b128 v[144:147], v151
	ds_read_b128 v[156:159], v151 offset:1024
	ds_read_b128 v[160:163], v151 offset:2048
	ds_read_b128 v[164:167], v151 offset:3072
	ds_read_b128 v[168:171], v152
	ds_read_b128 v[172:175], v152 offset:1024
	ds_read_b128 v[176:179], v152 offset:2048
	ds_read_b128 v[180:183], v152 offset:3072
	s_bitcmp1_b32 s66, 1
	s_mov_b32 s98, 0xfefe80
	s_cselect_b32 s98, 0xffff0080, s98
	s_cselect_b32 s99, -1, 0
	s_add_u32 s40, s38, s98
	s_addc_u32 s41, s39, s99
	s_cmp_eq_u32 s66, 60
	s_cselect_b32 s43, s23, s41
	s_cselect_b32 s42, s37, s40
	s_cselect_b32 s41, s25, s65
	s_cselect_b32 s40, s63, s64
	v_lshl_add_u64 v[188:189], s[38:39], 0, v[136:137]
	s_add_i32 m0, s29, 0xc000
	ds_read_b128 v[184:187], v153
	ds_read_b128 v[194:197], v153 offset:1024
	ds_read_b128 v[198:201], v153 offset:2048
	ds_read_b128 v[202:205], v153 offset:3072
	ds_read_b128 v[206:209], v153 offset:4096
	ds_read_b128 v[210:213], v153 offset:5120
	ds_read_b128 v[214:217], v153 offset:6144
	ds_read_b128 v[218:221], v153 offset:7168
	global_load_lds_dwordx4 v[188:189], off
	v_lshl_add_u64 v[188:189], s[38:39], 0, v[138:139]
	s_add_i32 m0, s29, 0xe000
	s_nop 0
	global_load_lds_dwordx4 v[188:189], off
	s_waitcnt vmcnt(8)
	s_waitcnt lgkmcnt(0)
	s_barrier
	s_setprio 1
	s_waitcnt lgkmcnt(0)
	v_mfma_f32_16x16x32_bf16 v[124:127], v[144:147], v[184:187], v[124:127]
	v_mfma_f32_16x16x32_bf16 v[120:123], v[160:163], v[184:187], v[120:123]
	v_mfma_f32_16x16x32_bf16 v[108:111], v[144:147], v[198:201], v[108:111]
	v_mfma_f32_16x16x32_bf16 v[104:107], v[160:163], v[198:201], v[104:107]
	v_mfma_f32_16x16x32_bf16 v[92:95], v[144:147], v[206:209], v[92:95]
	v_mfma_f32_16x16x32_bf16 v[88:91], v[160:163], v[206:209], v[88:91]
	v_mfma_f32_16x16x32_bf16 v[76:79], v[144:147], v[214:217], v[76:79]
	v_mfma_f32_16x16x32_bf16 v[72:75], v[160:163], v[214:217], v[72:75]
	v_mfma_f32_16x16x32_bf16 v[124:127], v[156:159], v[194:197], v[124:127]
	v_mfma_f32_16x16x32_bf16 v[120:123], v[164:167], v[194:197], v[120:123]
	v_mfma_f32_16x16x32_bf16 v[108:111], v[156:159], v[202:205], v[108:111]
	v_mfma_f32_16x16x32_bf16 v[104:107], v[164:167], v[202:205], v[104:107]
	v_mfma_f32_16x16x32_bf16 v[92:95], v[156:159], v[210:213], v[92:95]
	v_mfma_f32_16x16x32_bf16 v[88:91], v[164:167], v[210:213], v[88:91]
	v_mfma_f32_16x16x32_bf16 v[76:79], v[156:159], v[218:221], v[76:79]
	v_mfma_f32_16x16x32_bf16 v[72:75], v[164:167], v[218:221], v[72:75]
	s_setprio 0
	s_setprio 1
	v_mfma_f32_16x16x32_bf16 v[116:119], v[168:171], v[184:187], v[116:119]
	v_mfma_f32_16x16x32_bf16 v[112:115], v[176:179], v[184:187], v[112:115]
	v_mfma_f32_16x16x32_bf16 v[100:103], v[168:171], v[198:201], v[100:103]
	v_mfma_f32_16x16x32_bf16 v[96:99], v[176:179], v[198:201], v[96:99]
	v_mfma_f32_16x16x32_bf16 v[84:87], v[168:171], v[206:209], v[84:87]
	v_mfma_f32_16x16x32_bf16 v[80:83], v[176:179], v[206:209], v[80:83]
	v_mfma_f32_16x16x32_bf16 v[68:71], v[168:171], v[214:217], v[68:71]
	v_mfma_f32_16x16x32_bf16 v[64:67], v[176:179], v[214:217], v[64:67]
	v_mfma_f32_16x16x32_bf16 v[116:119], v[172:175], v[194:197], v[116:119]
	v_mfma_f32_16x16x32_bf16 v[112:115], v[180:183], v[194:197], v[112:115]
	v_mfma_f32_16x16x32_bf16 v[100:103], v[172:175], v[202:205], v[100:103]
	v_mfma_f32_16x16x32_bf16 v[96:99], v[180:183], v[202:205], v[96:99]
	v_mfma_f32_16x16x32_bf16 v[84:87], v[172:175], v[210:213], v[84:87]
	v_mfma_f32_16x16x32_bf16 v[80:83], v[180:183], v[210:213], v[80:83]
	v_mfma_f32_16x16x32_bf16 v[68:71], v[172:175], v[218:221], v[68:71]
	v_mfma_f32_16x16x32_bf16 v[64:67], v[180:183], v[218:221], v[64:67]
	s_setprio 0
	s_barrier
	s_add_i32 s67, s50, s3
	v_lshl_add_u64 v[188:189], s[40:41], 0, v[130:131]
	s_mov_b32 m0, s67
	ds_read_b128 v[184:187], v153 offset:16384
	ds_read_b128 v[194:197], v153 offset:17408
	ds_read_b128 v[198:201], v153 offset:18432
	ds_read_b128 v[202:205], v153 offset:19456
	ds_read_b128 v[206:209], v153 offset:20480
	ds_read_b128 v[210:213], v153 offset:21504
	ds_read_b128 v[214:217], v153 offset:22528
	ds_read_b128 v[218:221], v153 offset:23552
	global_load_lds_dwordx4 v[188:189], off
	s_add_i32 m0, s67, 0x2000
	s_add_u32 s68, s40, 0x100000
	v_lshl_add_u64 v[222:223], s[40:41], 0, v[134:135]
	s_addc_u32 s69, s41, 0
	s_add_i32 s67, s51, s3
	global_load_lds_dwordx4 v[222:223], off
	v_lshl_add_u64 v[224:225], s[68:69], 0, v[130:131]
	s_mov_b32 m0, s67
	v_lshl_add_u64 v[226:227], s[42:43], 0, v[132:133]
	global_load_lds_dwordx4 v[224:225], off
	v_lshl_add_u64 v[224:225], s[68:69], 0, v[134:135]
	s_add_i32 m0, s67, 0x2000
	s_nop 0
	global_load_lds_dwordx4 v[224:225], off
	v_lshl_add_u64 v[224:225], s[42:43], 0, v[128:129]
	s_mov_b32 m0, s29
	s_nop 0
	global_load_lds_dwordx4 v[224:225], off
	s_mov_b32 m0, s30
	s_nop 0
	global_load_lds_dwordx4 v[226:227], off
	s_waitcnt vmcnt(8)
	s_waitcnt lgkmcnt(0)
	s_barrier
	s_setprio 1
	s_waitcnt lgkmcnt(0)
	v_mfma_f32_16x16x32_bf16 v[60:63], v[144:147], v[184:187], v[60:63]
	v_mfma_f32_16x16x32_bf16 v[56:59], v[160:163], v[184:187], v[56:59]
	v_mfma_f32_16x16x32_bf16 v[44:47], v[144:147], v[198:201], v[44:47]
	v_mfma_f32_16x16x32_bf16 v[40:43], v[160:163], v[198:201], v[40:43]
	v_mfma_f32_16x16x32_bf16 v[28:31], v[144:147], v[206:209], v[28:31]
	v_mfma_f32_16x16x32_bf16 v[24:27], v[160:163], v[206:209], v[24:27]
	v_mfma_f32_16x16x32_bf16 v[12:15], v[144:147], v[214:217], v[12:15]
	v_mfma_f32_16x16x32_bf16 v[8:11], v[160:163], v[214:217], v[8:11]
	v_mfma_f32_16x16x32_bf16 v[60:63], v[156:159], v[194:197], v[60:63]
	v_mfma_f32_16x16x32_bf16 v[56:59], v[164:167], v[194:197], v[56:59]
	v_mfma_f32_16x16x32_bf16 v[44:47], v[156:159], v[202:205], v[44:47]
	v_mfma_f32_16x16x32_bf16 v[40:43], v[164:167], v[202:205], v[40:43]
	v_mfma_f32_16x16x32_bf16 v[28:31], v[156:159], v[210:213], v[28:31]
	v_mfma_f32_16x16x32_bf16 v[24:27], v[164:167], v[210:213], v[24:27]
	v_mfma_f32_16x16x32_bf16 v[12:15], v[156:159], v[218:221], v[12:15]
	v_mfma_f32_16x16x32_bf16 v[8:11], v[164:167], v[218:221], v[8:11]
	s_setprio 0
	s_setprio 1
	v_mfma_f32_16x16x32_bf16 v[52:55], v[168:171], v[184:187], v[52:55]
	v_mfma_f32_16x16x32_bf16 v[48:51], v[176:179], v[184:187], v[48:51]
	v_mfma_f32_16x16x32_bf16 v[36:39], v[168:171], v[198:201], v[36:39]
	v_mfma_f32_16x16x32_bf16 v[32:35], v[176:179], v[198:201], v[32:35]
	v_mfma_f32_16x16x32_bf16 v[20:23], v[168:171], v[206:209], v[20:23]
	v_mfma_f32_16x16x32_bf16 v[16:19], v[176:179], v[206:209], v[16:19]
	v_mfma_f32_16x16x32_bf16 v[4:7], v[168:171], v[214:217], v[4:7]
	v_mfma_f32_16x16x32_bf16 v[0:3], v[176:179], v[214:217], v[0:3]
	v_mfma_f32_16x16x32_bf16 v[52:55], v[172:175], v[194:197], v[52:55]
	v_mfma_f32_16x16x32_bf16 v[48:51], v[180:183], v[194:197], v[48:51]
	v_mfma_f32_16x16x32_bf16 v[36:39], v[172:175], v[202:205], v[36:39]
	v_mfma_f32_16x16x32_bf16 v[32:35], v[180:183], v[202:205], v[32:35]
	v_mfma_f32_16x16x32_bf16 v[20:23], v[172:175], v[210:213], v[20:23]
	v_mfma_f32_16x16x32_bf16 v[16:19], v[180:183], v[210:213], v[16:19]
	v_mfma_f32_16x16x32_bf16 v[4:7], v[172:175], v[218:221], v[4:7]
	v_mfma_f32_16x16x32_bf16 v[0:3], v[180:183], v[218:221], v[0:3]
	s_setprio 0
	s_barrier
	s_add_i32 s67, 0, 0x18000
	v_add_u32_e32 v155, s67, v149
	s_add_i32 s68, 0, 0x1c000
	ds_read_b128 v[144:147], v155
	ds_read_b128 v[156:159], v155 offset:1024
	ds_read_b128 v[160:163], v155 offset:2048
	ds_read_b128 v[164:167], v155 offset:3072
	v_add_u32_e32 v155, s68, v149
	ds_read_b128 v[168:171], v155
	ds_read_b128 v[172:175], v155 offset:1024
	ds_read_b128 v[176:179], v155 offset:2048
	ds_read_b128 v[180:183], v155 offset:3072
	s_add_u32 s42, s42, 0x10000
	s_addc_u32 s43, s43, 0
	s_mov_b32 m0, s31
	v_lshl_add_u64 v[228:229], s[42:43], 0, v[128:129]
	ds_read_b128 v[184:187], v153 offset:32768
	ds_read_b128 v[194:197], v153 offset:33792
	ds_read_b128 v[198:201], v153 offset:34816
	ds_read_b128 v[202:205], v153 offset:35840
	ds_read_b128 v[206:209], v153 offset:36864
	ds_read_b128 v[210:213], v153 offset:37888
	ds_read_b128 v[214:217], v153 offset:38912
	ds_read_b128 v[218:221], v153 offset:39936
	global_load_lds_dwordx4 v[228:229], off
	v_lshl_add_u64 v[228:229], s[42:43], 0, v[132:133]
	s_mov_b32 m0, s33
	s_nop 0
	global_load_lds_dwordx4 v[228:229], off
	s_waitcnt vmcnt(8)
	s_waitcnt lgkmcnt(0)
	s_barrier
	s_setprio 1
	s_waitcnt lgkmcnt(0)
	v_mfma_f32_16x16x32_bf16 v[124:127], v[144:147], v[184:187], v[124:127]
	v_mfma_f32_16x16x32_bf16 v[120:123], v[160:163], v[184:187], v[120:123]
	v_mfma_f32_16x16x32_bf16 v[108:111], v[144:147], v[198:201], v[108:111]
	v_mfma_f32_16x16x32_bf16 v[104:107], v[160:163], v[198:201], v[104:107]
	v_mfma_f32_16x16x32_bf16 v[92:95], v[144:147], v[206:209], v[92:95]
	v_mfma_f32_16x16x32_bf16 v[88:91], v[160:163], v[206:209], v[88:91]
	v_mfma_f32_16x16x32_bf16 v[76:79], v[144:147], v[214:217], v[76:79]
	v_mfma_f32_16x16x32_bf16 v[72:75], v[160:163], v[214:217], v[72:75]
	v_mfma_f32_16x16x32_bf16 v[124:127], v[156:159], v[194:197], v[124:127]
	v_mfma_f32_16x16x32_bf16 v[120:123], v[164:167], v[194:197], v[120:123]
	v_mfma_f32_16x16x32_bf16 v[108:111], v[156:159], v[202:205], v[108:111]
	v_mfma_f32_16x16x32_bf16 v[104:107], v[164:167], v[202:205], v[104:107]
	v_mfma_f32_16x16x32_bf16 v[92:95], v[156:159], v[210:213], v[92:95]
	v_mfma_f32_16x16x32_bf16 v[88:91], v[164:167], v[210:213], v[88:91]
	v_mfma_f32_16x16x32_bf16 v[76:79], v[156:159], v[218:221], v[76:79]
	v_mfma_f32_16x16x32_bf16 v[72:75], v[164:167], v[218:221], v[72:75]
	s_setprio 0
	s_setprio 1
	v_mfma_f32_16x16x32_bf16 v[116:119], v[168:171], v[184:187], v[116:119]
	v_mfma_f32_16x16x32_bf16 v[112:115], v[176:179], v[184:187], v[112:115]
	v_mfma_f32_16x16x32_bf16 v[100:103], v[168:171], v[198:201], v[100:103]
	v_mfma_f32_16x16x32_bf16 v[96:99], v[176:179], v[198:201], v[96:99]
	v_mfma_f32_16x16x32_bf16 v[84:87], v[168:171], v[206:209], v[84:87]
	v_mfma_f32_16x16x32_bf16 v[80:83], v[176:179], v[206:209], v[80:83]
	v_mfma_f32_16x16x32_bf16 v[68:71], v[168:171], v[214:217], v[68:71]
	v_mfma_f32_16x16x32_bf16 v[64:67], v[176:179], v[214:217], v[64:67]
	v_mfma_f32_16x16x32_bf16 v[116:119], v[172:175], v[194:197], v[116:119]
	v_mfma_f32_16x16x32_bf16 v[112:115], v[180:183], v[194:197], v[112:115]
	v_mfma_f32_16x16x32_bf16 v[100:103], v[172:175], v[202:205], v[100:103]
	v_mfma_f32_16x16x32_bf16 v[96:99], v[180:183], v[202:205], v[96:99]
	v_mfma_f32_16x16x32_bf16 v[84:87], v[172:175], v[210:213], v[84:87]
	v_mfma_f32_16x16x32_bf16 v[80:83], v[180:183], v[210:213], v[80:83]
	v_mfma_f32_16x16x32_bf16 v[68:71], v[172:175], v[218:221], v[68:71]
	v_mfma_f32_16x16x32_bf16 v[64:67], v[180:183], v[218:221], v[64:67]
	s_setprio 0
	s_barrier
	s_add_i32 s42, s67, s3
	v_lshl_add_u64 v[188:189], v[188:189], 0, s[18:19]
	s_mov_b32 m0, s42
	ds_read_b128 v[184:187], v153 offset:49152
	ds_read_b128 v[194:197], v153 offset:50176
	ds_read_b128 v[198:201], v153 offset:51200
	ds_read_b128 v[202:205], v153 offset:52224
	ds_read_b128 v[206:209], v153 offset:53248
	ds_read_b128 v[210:213], v153 offset:54272
	ds_read_b128 v[214:217], v153 offset:55296
	ds_read_b128 v[218:221], v153 offset:56320
	global_load_lds_dwordx4 v[188:189], off
	s_add_i32 m0, s42, 0x2000
	s_add_u32 s40, s40, 0x100080
	v_lshl_add_u64 v[188:189], v[222:223], 0, s[18:19]
	s_addc_u32 s41, s41, 0
	s_add_i32 s42, s68, s3
	global_load_lds_dwordx4 v[188:189], off
	v_lshl_add_u64 v[188:189], s[40:41], 0, v[130:131]
	s_mov_b32 m0, s42
	s_nop 0
	global_load_lds_dwordx4 v[188:189], off
	v_lshl_add_u64 v[188:189], s[40:41], 0, v[134:135]
	s_add_i32 m0, s42, 0x2000
	s_nop 0
	global_load_lds_dwordx4 v[188:189], off
	v_lshl_add_u64 v[188:189], v[224:225], 0, s[18:19]
	s_mov_b32 m0, s46
	s_nop 0
	global_load_lds_dwordx4 v[188:189], off
	v_lshl_add_u64 v[188:189], v[226:227], 0, s[18:19]
	s_mov_b32 m0, s47
	s_nop 0
	global_load_lds_dwordx4 v[188:189], off
	s_waitcnt vmcnt(8)
	s_waitcnt lgkmcnt(0)
	s_barrier
	s_setprio 1
	s_waitcnt lgkmcnt(0)
	v_mfma_f32_16x16x32_bf16 v[60:63], v[144:147], v[184:187], v[60:63]
	v_mfma_f32_16x16x32_bf16 v[56:59], v[160:163], v[184:187], v[56:59]
	v_mfma_f32_16x16x32_bf16 v[44:47], v[144:147], v[198:201], v[44:47]
	v_mfma_f32_16x16x32_bf16 v[40:43], v[160:163], v[198:201], v[40:43]
	v_mfma_f32_16x16x32_bf16 v[28:31], v[144:147], v[206:209], v[28:31]
	v_mfma_f32_16x16x32_bf16 v[24:27], v[160:163], v[206:209], v[24:27]
	v_mfma_f32_16x16x32_bf16 v[12:15], v[144:147], v[214:217], v[12:15]
	v_mfma_f32_16x16x32_bf16 v[8:11], v[160:163], v[214:217], v[8:11]
	v_mfma_f32_16x16x32_bf16 v[60:63], v[156:159], v[194:197], v[60:63]
	v_mfma_f32_16x16x32_bf16 v[56:59], v[164:167], v[194:197], v[56:59]
	v_mfma_f32_16x16x32_bf16 v[44:47], v[156:159], v[202:205], v[44:47]
	v_mfma_f32_16x16x32_bf16 v[40:43], v[164:167], v[202:205], v[40:43]
	v_mfma_f32_16x16x32_bf16 v[28:31], v[156:159], v[210:213], v[28:31]
	v_mfma_f32_16x16x32_bf16 v[24:27], v[164:167], v[210:213], v[24:27]
	v_mfma_f32_16x16x32_bf16 v[12:15], v[156:159], v[218:221], v[12:15]
	v_mfma_f32_16x16x32_bf16 v[8:11], v[164:167], v[218:221], v[8:11]
	s_setprio 0
	s_setprio 1
	v_mfma_f32_16x16x32_bf16 v[52:55], v[168:171], v[184:187], v[52:55]
	v_mfma_f32_16x16x32_bf16 v[48:51], v[176:179], v[184:187], v[48:51]
	v_mfma_f32_16x16x32_bf16 v[36:39], v[168:171], v[198:201], v[36:39]
	v_mfma_f32_16x16x32_bf16 v[32:35], v[176:179], v[198:201], v[32:35]
	v_mfma_f32_16x16x32_bf16 v[20:23], v[168:171], v[206:209], v[20:23]
	v_mfma_f32_16x16x32_bf16 v[16:19], v[176:179], v[206:209], v[16:19]
	v_mfma_f32_16x16x32_bf16 v[4:7], v[168:171], v[214:217], v[4:7]
	v_mfma_f32_16x16x32_bf16 v[0:3], v[176:179], v[214:217], v[0:3]
	v_mfma_f32_16x16x32_bf16 v[52:55], v[172:175], v[194:197], v[52:55]
	v_mfma_f32_16x16x32_bf16 v[48:51], v[180:183], v[194:197], v[48:51]
	v_mfma_f32_16x16x32_bf16 v[36:39], v[172:175], v[202:205], v[36:39]
	v_mfma_f32_16x16x32_bf16 v[32:35], v[180:183], v[202:205], v[32:35]
	v_mfma_f32_16x16x32_bf16 v[20:23], v[172:175], v[210:213], v[20:23]
	v_mfma_f32_16x16x32_bf16 v[16:19], v[180:183], v[210:213], v[16:19]
	v_mfma_f32_16x16x32_bf16 v[4:7], v[172:175], v[218:221], v[4:7]
	v_mfma_f32_16x16x32_bf16 v[0:3], v[180:183], v[218:221], v[0:3]
	s_setprio 0
	s_barrier
	s_bitcmp1_b32 s66, 1
	s_mov_b32 s98, 0xffff00
	s_cselect_b32 s98, 0x100, s98
	s_add_i32 s66, s66, 2
	s_add_u32 s38, s38, s98
	s_addc_u32 s39, s39, 0
	s_add_u32 s64, s64, 0x100
	s_addc_u32 s65, s65, 0
	s_cmp_gt_u32 s66, 61
	s_cbranch_scc0 .LBB0_1326
	s_and_b64 vcc, exec, s[20:21]
	s_cbranch_vccz .LBB0_1329
	s_barrier
